# store_gated: four gate loads issued together, counted waits; ticket atomic before job barrier; init rope positions preloaded, rope/row pass order swapped for half the workgroups
# speedup vs baseline: 1.0052x; 1.0052x over previous
.LBB0_190:
	s_or_b64 exec, exec, s[8:9]
	s_mov_b32 s100, 0
	s_bitcmp1_b32 s64, 8
	s_cbranch_scc1 .Linit_g1
.Linit_rope:
	s_mov_b32 s0, 0xc0000
	v_cmp_gt_i32_e64 s[0:1], s0, v43
	s_and_saveexec_b64 s[12:13], s[0:1]
	s_cbranch_execz .LBB0_201
	s_add_u32 s14, s2, 0x1bc0000
	s_addc_u32 s15, s3, 0
	s_add_u32 s16, s2, 0x1cc0000
	s_addc_u32 s17, s3, 0
	s_add_u32 s18, s2, 0x17c0000
	s_mov_b32 s24, 0x979a371
	s_mov_b32 s26, 0x3b39803f
	s_mov_b32 s28, 0xfefa39ef
	s_mov_b32 s30, 0x6a5dcb37
	s_mov_b32 s34, 0
	s_mov_b32 s36, 0
	s_addc_u32 s19, s3, 0
	s_mov_b64 s[20:21], 0
	s_mov_b32 s39, 0x2aaaaaab
	s_movk_i32 s40, 0xffd0
	s_mov_b32 s23, 0xbfea934f
	s_mov_b32 s25, 0xbfda934f
	s_mov_b32 s27, 0x3c7abc9e
	s_mov_b32 s29, 0x3fe62e42
	v_mov_b32_e32 v0, 0xfca7ab0c
	v_mov_b32_e32 v1, 0x3e928af3
	s_mov_b32 s31, 0x3e5ade15
	v_mov_b32_e32 v2, 0x623fde64
	v_mov_b32_e32 v3, 0x3ec71dee
	v_mov_b32_e32 v4, 0x7c89e6b0
	v_mov_b32_e32 v5, 0x3efa0199
	v_mov_b32_e32 v6, 0x14761f6e
	v_mov_b32_e32 v7, 0x3f2a01a0
	v_mov_b32_e32 v8, 0x1852b7b0
	v_mov_b32_e32 v9, 0x3f56c16c
	v_mov_b32_e32 v10, 0x11122322
	v_mov_b32_e32 v11, 0x3f811111
	v_mov_b32_e32 v12, 0x555502a1
	v_mov_b32_e32 v13, 0x3fa55555
	v_mov_b32_e32 v14, 0x55555511
	v_mov_b32_e32 v15, 0x3fc55555
	v_mov_b32_e32 v16, 11
	v_mov_b32_e32 v17, 0x3fe00000
	s_mov_b32 s35, 0x40900000
	v_mov_b32_e32 v19, 0x7ff00000
	s_mov_b32 s37, 0xc090cc00
	s_mov_b32 s41, 0xbffff
	v_mov_b32_e32 v18, v43
	v_readlane_b32 s58, v252, 24
	v_readlane_b32 s59, v252, 25
	v_mov_b32_e32 v36, v18
	v_min_i32_e32 v37, s41, v36
	v_mul_hi_i32 v38, v37, s39
	v_lshrrev_b32_e32 v39, 31, v38
	v_ashrrev_i32_e32 v38, 3, v38
	v_add_u32_e32 v38, v38, v39
	v_ashrrev_i32_e32 v39, 31, v38
	v_lshl_add_u64 v[38:39], v[38:39], 2, s[58:59]
	global_load_dword v30, v[38:39], off
	v_add_u32_e32 v36, s38, v36
	v_min_i32_e32 v37, s41, v36
	v_mul_hi_i32 v38, v37, s39
	v_lshrrev_b32_e32 v39, 31, v38
	v_ashrrev_i32_e32 v38, 3, v38
	v_add_u32_e32 v38, v38, v39
	v_ashrrev_i32_e32 v39, 31, v38
	v_lshl_add_u64 v[38:39], v[38:39], 2, s[58:59]
	global_load_dword v31, v[38:39], off
	v_add_u32_e32 v36, s38, v36
	v_min_i32_e32 v37, s41, v36
	v_mul_hi_i32 v38, v37, s39
	v_lshrrev_b32_e32 v39, 31, v38
	v_ashrrev_i32_e32 v38, 3, v38
	v_add_u32_e32 v38, v38, v39
	v_ashrrev_i32_e32 v39, 31, v38
	v_lshl_add_u64 v[38:39], v[38:39], 2, s[58:59]
	global_load_dword v32, v[38:39], off
	v_add_u32_e32 v36, s38, v36
	v_min_i32_e32 v37, s41, v36
	v_mul_hi_i32 v38, v37, s39
	v_lshrrev_b32_e32 v39, 31, v38
	v_ashrrev_i32_e32 v38, 3, v38
	v_add_u32_e32 v38, v38, v39
	v_ashrrev_i32_e32 v39, 31, v38
	v_lshl_add_u64 v[38:39], v[38:39], 2, s[58:59]
	global_load_dword v33, v[38:39], off
	v_add_u32_e32 v36, s38, v36
	v_min_i32_e32 v37, s41, v36
	v_mul_hi_i32 v38, v37, s39
	v_lshrrev_b32_e32 v39, 31, v38
	v_ashrrev_i32_e32 v38, 3, v38
	v_add_u32_e32 v38, v38, v39
	v_ashrrev_i32_e32 v39, 31, v38
	v_lshl_add_u64 v[38:39], v[38:39], 2, s[58:59]
	global_load_dword v34, v[38:39], off
	v_add_u32_e32 v36, s38, v36
	v_min_i32_e32 v37, s41, v36
	v_mul_hi_i32 v38, v37, s39
	v_lshrrev_b32_e32 v39, 31, v38
	v_ashrrev_i32_e32 v38, 3, v38
	v_add_u32_e32 v38, v38, v39
	v_ashrrev_i32_e32 v39, 31, v38
	v_lshl_add_u64 v[38:39], v[38:39], 2, s[58:59]
	global_load_dword v35, v[38:39], off
	s_waitcnt vmcnt(0)
	s_branch .LBB0_193

.LBB0_193:
	v_mul_hi_i32 v20, v18, s39
	v_lshrrev_b32_e32 v21, 31, v20
	v_ashrrev_i32_e32 v20, 3, v20
	v_add_u32_e32 v20, v20, v21
	v_readlane_b32 s44, v252, 10
	v_ashrrev_i32_e32 v21, 31, v20
	v_readlane_b32 s58, v252, 24
	v_readlane_b32 s59, v252, 25
	v_mad_u64_u32 v[24:25], s[0:1], v20, s40, v[18:19]
	s_nop 0
	v_lshl_add_u64 v[22:23], v[20:21], 2, s[58:59]
	v_mov_b32_e32 v21, v30
	v_mov_b32_e32 v30, v31
	v_mov_b32_e32 v31, v32
	v_mov_b32_e32 v32, v33
	v_mov_b32_e32 v33, v34
	v_mov_b32_e32 v34, v35
	v_cmp_lt_i32_e64 s[0:1], 31, v24
	v_readlane_b32 s45, v252, 11
	v_readlane_b32 s46, v252, 12
	v_readlane_b32 s47, v252, 13
	v_readlane_b32 s48, v252, 14
	v_readlane_b32 s49, v252, 15
	v_readlane_b32 s50, v252, 16
	v_readlane_b32 s51, v252, 17
	v_readlane_b32 s52, v252, 18
	v_readlane_b32 s53, v252, 19
	v_readlane_b32 s54, v252, 20
	v_readlane_b32 s55, v252, 21
	v_readlane_b32 s56, v252, 22
	v_readlane_b32 s57, v252, 23
	s_and_saveexec_b64 s[8:9], s[0:1]
	s_xor_b64 s[8:9], exec, s[8:9]
	v_subrev_u32_e32 v22, 32, v24
	v_cvt_f64_u32_e32 v[22:23], v22
	s_mov_b32 s22, s24
	v_mul_f64 v[22:23], v[22:23], s[22:23]
	s_andn2_saveexec_b64 s[8:9], s[8:9]
	v_cvt_f64_i32_e32 v[22:23], v24
	v_mul_f64 v[22:23], v[22:23], s[24:25]
	s_or_b64 exec, exec, s[8:9]
	v_rndne_f64_e32 v[24:25], v[22:23]
	v_add_f64 v[26:27], v[22:23], -v[24:25]
	v_mul_f64 v[28:29], v[26:27], s[26:27]
	v_fmac_f64_e32 v[28:29], s[28:29], v[26:27]
	v_fma_f64 v[26:27], s[30:31], v[28:29], v[0:1]
	v_fma_f64 v[26:27], v[28:29], v[26:27], v[2:3]
	v_fma_f64 v[26:27], v[28:29], v[26:27], v[4:5]
	v_fma_f64 v[26:27], v[28:29], v[26:27], v[6:7]
	v_fma_f64 v[26:27], v[28:29], v[26:27], v[8:9]
	v_fma_f64 v[26:27], v[28:29], v[26:27], v[10:11]
	v_fma_f64 v[26:27], v[28:29], v[26:27], v[12:13]
	v_fma_f64 v[26:27], v[28:29], v[26:27], v[14:15]
	v_fma_f64 v[26:27], v[28:29], v[26:27], v[16:17]
	v_fma_f64 v[26:27], v[28:29], v[26:27], 1.0
	v_fma_f64 v[26:27], v[28:29], v[26:27], 1.0
	v_cvt_i32_f64_e32 v24, v[24:25]
	s_nop 0
	v_cvt_f32_i32_e32 v21, v21
	v_ldexp_f64 v[24:25], v[26:27], v24
	v_cmp_nlt_f64_e64 s[8:9], s[34:35], v[22:23]
	v_cmp_ngt_f64_e64 s[10:11], s[36:37], v[22:23]
	s_nop 0
	v_cndmask_b32_e64 v25, v19, v25, s[8:9]
	s_and_b64 s[8:9], s[10:11], s[8:9]
	v_cndmask_b32_e64 v23, 0, v25, s[10:11]
	v_cndmask_b32_e64 v22, 0, v24, s[8:9]
	v_cvt_f32_f64_e32 v22, v[22:23]
	v_mul_f32_e32 v21, v21, v22
	v_mul_f32_e32 v22, 0.15915494, v21
	v_floor_f32_e32 v22, v22
	v_fma_f32 v22, v21, 0.15915494, -v22
	v_sin_f32_e32 v21, v22
	v_cos_f32_e32 v22, v22
	s_and_saveexec_b64 s[8:9], s[0:1]
	s_xor_b64 s[0:1], exec, s[8:9]
	s_cbranch_execz .LBB0_199
	v_lshlrev_b32_e32 v20, 5, v20
	v_sub_u32_e32 v20, v18, v20
	v_subrev_u32_e32 v24, 32, v20
	v_ashrrev_i32_e32 v25, 31, v24
	v_lshlrev_b64 v[24:25], 2, v[24:25]
	v_lshl_add_u64 v[26:27], s[14:15], 0, v[24:25]
	global_store_dword v[26:27], v22, off
	v_lshl_add_u64 v[22:23], s[16:17], 0, v[24:25]
	global_store_dword v[22:23], v21, off

.LBB0_201:
	s_or_b64 exec, exec, s[12:13]
	s_cmp_lg_u32 s100, 0
	s_cbranch_scc1 .Linit_done
.Linit_g1:
	s_movk_i32 s0, 0x200
	v_cmp_gt_i32_e32 vcc, s0, v43
	s_and_saveexec_b64 s[0:1], vcc
	s_cbranch_execz .LBB0_204
	s_add_u32 s8, s2, 0xd1d0000
	s_addc_u32 s9, s3, 0
	v_readlane_b32 s12, v252, 2
	s_add_u32 s10, s2, 0xd1f0000
	v_mov_b32_e32 v0, 0x1fc0
	v_lshlrev_b32_e32 v1, 7, v42
	v_readlane_b32 s13, v252, 3
	v_readlane_b32 s14, v252, 4
	v_readlane_b32 s15, v252, 5
	v_readlane_b32 s18, v252, 8
	s_addc_u32 s11, s3, 0
	v_and_or_b32 v0, v42, 63, v0
	v_lshl_add_u32 v1, s64, 15, v1
	s_lshl_b32 s14, s18, 15
	s_mov_b64 s[12:13], 0
	v_mov_b32_e32 v2, 0
	s_movk_i32 s15, 0x1ff
	v_readlane_b32 s16, v252, 6
	v_readlane_b32 s17, v252, 7
	v_readlane_b32 s19, v252, 9

.LBB0_209:
	s_or_b64 exec, exec, s[8:9]
	s_bitcmp1_b32 s64, 8
	s_cbranch_scc0 .Linit_done
	s_mov_b32 s100, 1
	v_lshl_add_u32 v43, s64, 8, v42
	s_branch .Linit_rope
.Linit_done:
	s_waitcnt vmcnt(0)
	s_waitcnt lgkmcnt(0)
	s_barrier
	s_and_saveexec_b64 s[0:1], s[66:67]
	s_cbranch_execz .LBB0_261
	v_mov_b32_e32 v0, 0x12400
	s_waitcnt vmcnt(0) expcnt(0) lgkmcnt(0)
	ds_read_b32 v2, v0
	v_mov_b32_e32 v0, 0x12404
	v_mov_b32_e32 v1, 0x12408
	ds_read_b32 v0, v0
	ds_read_b32 v1, v1
	s_waitcnt lgkmcnt(2)
	v_cmp_ne_u32_e32 vcc, 0, v2
	s_waitcnt lgkmcnt(0)
	v_readfirstlane_b32 s48, v1
	s_cbranch_vccnz .LBB0_225
	v_readlane_b32 s40, v252, 2
	v_readlane_b32 s42, v252, 4
	v_readlane_b32 s43, v252, 5
	s_add_u32 s2, s42, 0xf210200
	s_addc_u32 s3, s43, 0
	s_add_u32 s8, s42, 0xf210400
	s_addc_u32 s9, s43, 0
	s_add_u32 s10, s42, 0xf210500
	s_addc_u32 s11, s43, 0
	s_add_u32 s12, s42, 0xf210600
	s_addc_u32 s13, s43, 0
	s_add_u32 s14, s42, 0xf210700
	s_addc_u32 s15, s43, 0
	s_add_u32 s16, s42, 0xf210800
	s_addc_u32 s17, s43, 0
	s_add_u32 s18, s42, 0xf210900
	s_addc_u32 s19, s43, 0
	s_add_u32 s20, s42, 0xf210a00
	s_addc_u32 s21, s43, 0
	s_add_u32 s22, s42, 0xf210b00
	s_addc_u32 s23, s43, 0
	s_add_u32 s24, s42, 0xf210c00
	s_addc_u32 s25, s43, 0
	s_add_u32 s26, s42, 0xf210d00
	s_addc_u32 s27, s43, 0
	s_add_u32 s28, s42, 0xf210e00
	s_addc_u32 s29, s43, 0
	s_add_u32 s30, s42, 0xf210f00
	s_addc_u32 s31, s43, 0
	s_add_u32 s34, s42, 0xf211000
	s_addc_u32 s35, s43, 0
	s_add_u32 s36, s42, 0xf211100
	s_addc_u32 s37, s43, 0
	s_add_u32 s38, s42, 0xf211200
	v_readlane_b32 s47, v252, 9
	s_addc_u32 s39, s43, 0
	v_readlane_b32 s41, v252, 3
	v_readlane_b32 s46, v252, 8
	s_mul_i32 s49, s47, s33
	s_add_u32 s40, s42, 0xf211300
	s_mul_i32 s49, s49, s46
	s_addc_u32 s41, s43, 0
	s_mov_b32 s50, 1
	v_mov_b32_e32 v16, 0
	v_readlane_b32 s44, v252, 6
	v_readlane_b32 s45, v252, 7
	s_branch .LBB0_213

.LBB0_374:
	v_mov_b32_e32 v198, v234
	s_nop 0
	v_cmp_eq_u32_e64 s[0:1], 0, v198
	s_and_saveexec_b64 s[8:9], s[0:1]
	s_cbranch_execz .Ljq_issued
	v_readlane_b32 s10, v253, 59
	v_readlane_b32 s11, v253, 60
	s_nop 1
	v_mov_b64_e32 v[0:1], s[10:11]
	global_atomic_add v0, v[0:1], v251, off sc0
.Ljq_issued:
	s_or_b64 exec, exec, s[8:9]
	s_barrier
	s_and_saveexec_b64 s[8:9], s[0:1]
	s_cbranch_execz .LBB0_376
	s_waitcnt vmcnt(0) lgkmcnt(0)
	ds_write_b32 v222, v0

.LBB0_411:
	v_mbcnt_lo_u32_b32 v0, -1, 0
	v_mbcnt_hi_u32_b32 v0, -1, v0
	v_and_b32_e32 v2, 64, v0
	v_xor_b32_e32 v1, 32, v0
	v_add_u32_e32 v2, 64, v2
	v_cmp_lt_i32_e32 vcc, v1, v2
	s_movk_i32 s8, 0x1d00
	v_mov_b32_e32 v141, v193
	v_cndmask_b32_e32 v0, v0, v1, vcc
	v_lshlrev_b32_e32 v0, 2, v0
	ds_bpermute_b32 v0, v0, v163
	s_waitcnt lgkmcnt(0)
	v_add_f32_e32 v0, v163, v0
	v_div_scale_f32 v1, s[0:1], v0, v0, 1.0
	v_rcp_f32_e32 v2, v1
	v_readlane_b32 s0, v254, 43
	v_readlane_b32 s1, v254, 44
	v_fma_f32 v3, -v1, v2, 1.0
	v_fmac_f32_e32 v2, v3, v2
	v_div_scale_f32 v3, vcc, 1.0, v0, 1.0
	v_mul_f32_e32 v4, v3, v2
	v_fma_f32 v5, -v1, v4, v3
	v_fmac_f32_e32 v4, v5, v2
	v_fma_f32 v1, -v1, v4, v3
	v_div_fmas_f32 v1, v1, v2, v4
	v_div_fixup_f32 v4, v1, v0, 1.0
	v_mov_b64_e32 v[0:1], s[0:1]
	v_mad_u64_u32 v[0:1], s[0:1], v142, s8, v[0:1]
	v_mad_i32_i24 v1, v143, s8, v1
	s_mov_b64 s[8:9], 0x3e38aa3b
	s_lshl_b32 s0, s10, 1
	s_mov_b32 s1, s9
	s_movk_i32 s10, 0xeb00
	v_lshl_add_u64 v[2:3], v[0:1], 0, s[0:1]
	v_mad_u64_u32 v[0:1], s[8:9], v142, s10, v[0:1]
	v_mad_i32_i24 v1, v143, s10, v1
	v_sub_u32_e32 v1, v1, v142
	v_lshl_add_u64 v[6:7], v[0:1], 0, s[0:1]
	v_lshl_add_u64 v[2:3], v[2:3], 0, v[140:141]
	s_mov_b64 s[0:1], 0x3dd0b00
	v_lshl_add_u64 v[0:1], v[2:3], 0, s[0:1]
	v_lshl_add_u64 v[12:13], v[6:7], 0, v[140:141]
	s_mov_b64 s[0:1], 0xd210200
	v_lshl_add_u64 v[6:7], v[12:13], 0, s[0:1]
	s_mov_b32 s0, 0x3dd0000
	v_add_co_u32_e32 v2, vcc, s0, v2
	v_readlane_b32 s10, v254, 51
	s_nop 0
	v_addc_co_u32_e32 v3, vcc, 0, v3, vcc
	global_load_dwordx4 v[8:11], v[2:3], off offset:2816
	global_load_dwordx4 v[64:67], v[0:1], off offset:32
	global_load_dwordx4 v[68:71], v[0:1], off offset:64
	global_load_dwordx4 v[72:75], v[0:1], off offset:96
	s_waitcnt vmcnt(3)
	v_mov_b32_e32 v5, v10
	s_nop 1
	v_permlane32_swap_b32_e32 v8, v5
	v_lshlrev_b32_e32 v14, 16, v8
	v_and_b32_e32 v8, 0xffff0000, v8
	v_mov_b32_e32 v16, v11
	v_mul_f32_e32 v10, 0xbfb8aa3b, v14
	v_mul_f32_e32 v11, 0xbfb8aa3b, v8
	v_exp_f32_e32 v10, v10
	v_exp_f32_e32 v11, v11
	v_permlane32_swap_b32_e32 v9, v16
	v_pk_mul_f32 v[2:3], v[48:49], v[4:5] op_sel_hi:[1,0]
	v_pk_add_f32 v[10:11], v[10:11], 1.0 op_sel_hi:[1,0]
	s_nop 0
	v_div_scale_f32 v15, s[0:1], v11, v11, v8
	v_rcp_f32_e32 v17, v15
	s_nop 0
	v_fma_f32 v18, -v15, v17, 1.0
	v_fmac_f32_e32 v17, v18, v17
	v_div_scale_f32 v18, vcc, v8, v11, v8
	v_mul_f32_e32 v19, v18, v17
	v_fma_f32 v20, -v15, v19, v18
	v_fmac_f32_e32 v19, v20, v17
	v_fma_f32 v15, -v15, v19, v18
	v_div_fmas_f32 v15, v15, v17, v19
	v_div_fixup_f32 v11, v15, v11, v8
	v_div_scale_f32 v8, s[0:1], v10, v10, v14
	v_rcp_f32_e32 v15, v8
	s_nop 0
	v_fma_f32 v17, -v8, v15, 1.0
	v_fmac_f32_e32 v15, v17, v15
	v_div_scale_f32 v17, vcc, v14, v10, v14
	v_mul_f32_e32 v18, v17, v15
	v_fma_f32 v19, -v8, v18, v17
	v_fmac_f32_e32 v18, v19, v15
	v_fma_f32 v8, -v8, v18, v17
	v_div_fmas_f32 v8, v8, v15, v18
	v_div_fixup_f32 v10, v8, v10, v14
	v_lshlrev_b32_e32 v14, 16, v9
	v_and_b32_e32 v15, 0xffff0000, v9
	v_pk_mul_f32 v[2:3], v[2:3], v[10:11]
	v_mul_f32_e32 v10, 0xbfb8aa3b, v14
	v_mul_f32_e32 v11, 0xbfb8aa3b, v15
	v_exp_f32_e32 v10, v10
	v_exp_f32_e32 v11, v11
	v_pk_mul_f32 v[8:9], v[50:51], v[4:5] op_sel_hi:[1,0]
	v_pk_add_f32 v[10:11], v[10:11], 1.0 op_sel_hi:[1,0]
	s_nop 0
	v_div_scale_f32 v17, s[0:1], v11, v11, v15
	v_rcp_f32_e32 v18, v17
	s_nop 0
	v_fma_f32 v19, -v17, v18, 1.0
	v_fmac_f32_e32 v18, v19, v18
	v_div_scale_f32 v19, vcc, v15, v11, v15
	v_mul_f32_e32 v20, v19, v18
	v_fma_f32 v21, -v17, v20, v19
	v_fmac_f32_e32 v20, v21, v18
	v_fma_f32 v17, -v17, v20, v19
	v_div_fmas_f32 v17, v17, v18, v20
	v_div_fixup_f32 v11, v17, v11, v15
	v_div_scale_f32 v15, s[0:1], v10, v10, v14
	v_rcp_f32_e32 v17, v15
	s_nop 0
	v_fma_f32 v18, -v15, v17, 1.0
	v_fmac_f32_e32 v17, v18, v17
	v_div_scale_f32 v18, vcc, v14, v10, v14
	v_mul_f32_e32 v19, v18, v17
	v_fma_f32 v20, -v15, v19, v18
	v_fmac_f32_e32 v19, v20, v17
	v_fma_f32 v15, -v15, v19, v18
	v_div_fmas_f32 v15, v15, v17, v19
	v_lshlrev_b32_e32 v17, 16, v5
	v_and_b32_e32 v5, 0xffff0000, v5
	v_div_fixup_f32 v10, v15, v10, v14
	v_mul_f32_e32 v14, 0xbfb8aa3b, v17
	v_mul_f32_e32 v15, 0xbfb8aa3b, v5
	v_exp_f32_e32 v14, v14
	v_exp_f32_e32 v15, v15
	v_pk_mul_f32 v[10:11], v[8:9], v[10:11]
	v_pk_mul_f32 v[8:9], v[52:53], v[4:5] op_sel_hi:[1,0]
	v_pk_add_f32 v[14:15], v[14:15], 1.0 op_sel_hi:[1,0]
	s_nop 0
	v_div_scale_f32 v18, s[0:1], v15, v15, v5
	v_rcp_f32_e32 v19, v18
	s_nop 0
	v_fma_f32 v20, -v18, v19, 1.0
	v_fmac_f32_e32 v19, v20, v19
	v_div_scale_f32 v20, vcc, v5, v15, v5
	v_mul_f32_e32 v21, v20, v19
	v_fma_f32 v22, -v18, v21, v20
	v_fmac_f32_e32 v21, v22, v19
	v_fma_f32 v18, -v18, v21, v20
	v_div_fmas_f32 v18, v18, v19, v21
	v_div_fixup_f32 v15, v18, v15, v5
	v_div_scale_f32 v5, s[0:1], v14, v14, v17
	v_rcp_f32_e32 v18, v5
	s_nop 0
	v_fma_f32 v19, -v5, v18, 1.0
	v_fmac_f32_e32 v18, v19, v18
	v_div_scale_f32 v19, vcc, v17, v14, v17
	v_mul_f32_e32 v20, v19, v18
	v_fma_f32 v21, -v5, v20, v19
	v_fmac_f32_e32 v20, v21, v18
	v_fma_f32 v5, -v5, v20, v19
	v_div_fmas_f32 v5, v5, v18, v20
	v_div_fixup_f32 v14, v5, v14, v17
	v_lshlrev_b32_e32 v5, 16, v16
	v_and_b32_e32 v18, 0xffff0000, v16
	v_mul_f32_e32 v16, 0xbfb8aa3b, v5
	v_mul_f32_e32 v17, 0xbfb8aa3b, v18
	v_exp_f32_e32 v16, v16
	v_exp_f32_e32 v17, v17
	v_pk_mul_f32 v[14:15], v[8:9], v[14:15]
	v_pk_mul_f32 v[8:9], v[54:55], v[4:5] op_sel_hi:[1,0]
	v_pk_add_f32 v[16:17], v[16:17], 1.0 op_sel_hi:[1,0]
	s_nop 0
	v_div_scale_f32 v19, s[0:1], v17, v17, v18
	v_rcp_f32_e32 v20, v19
	s_nop 0
	v_fma_f32 v21, -v19, v20, 1.0
	v_fmac_f32_e32 v20, v21, v20
	v_div_scale_f32 v21, vcc, v18, v17, v18
	v_mul_f32_e32 v22, v21, v20
	v_fma_f32 v23, -v19, v22, v21
	v_fmac_f32_e32 v22, v23, v20
	v_fma_f32 v19, -v19, v22, v21
	v_div_fmas_f32 v19, v19, v20, v22
	v_div_fixup_f32 v17, v19, v17, v18
	v_div_scale_f32 v18, s[0:1], v16, v16, v5
	v_rcp_f32_e32 v19, v18
	s_mov_b32 s0, 0xd210000
	v_fma_f32 v20, -v18, v19, 1.0
	v_fmac_f32_e32 v19, v20, v19
	v_div_scale_f32 v20, vcc, v5, v16, v5
	v_mul_f32_e32 v21, v20, v19
	v_fma_f32 v22, -v18, v21, v20
	v_fmac_f32_e32 v21, v22, v19
	v_fma_f32 v18, -v18, v21, v20
	v_div_fmas_f32 v18, v18, v19, v21
	v_div_fixup_f32 v16, v18, v16, v5
	v_pk_mul_f32 v[16:17], v[8:9], v[16:17]
	v_cvt_pk_bf16_f32 v8, v2, v3
	v_cvt_pk_bf16_f32 v9, v10, v11
	v_cvt_pk_bf16_f32 v10, v14, v15
	v_cvt_pk_bf16_f32 v11, v16, v17
	v_add_co_u32_e32 v2, vcc, s0, v12
	v_permlane32_swap_b32_e32 v8, v10
	v_permlane32_swap_b32_e32 v9, v11
	v_addc_co_u32_e32 v3, vcc, 0, v13, vcc
	global_store_dwordx4 v[2:3], v[8:11], off offset:512
	s_waitcnt vmcnt(3)
	v_mov_b32_e32 v5, v66
	s_nop 1
	v_mov_b32_e32 v8, v64
	s_nop 1
	v_permlane32_swap_b32_e32 v8, v5
	v_lshlrev_b32_e32 v12, 16, v8
	v_and_b32_e32 v8, 0xffff0000, v8
	v_mov_b32_e32 v14, v67
	v_mul_f32_e32 v10, 0xbfb8aa3b, v12
	v_mul_f32_e32 v11, 0xbfb8aa3b, v8
	v_exp_f32_e32 v10, v10
	v_exp_f32_e32 v11, v11
	v_mov_b32_e32 v9, v65
	s_nop 1
	v_permlane32_swap_b32_e32 v9, v14
	v_pk_mul_f32 v[2:3], v[56:57], v[4:5] op_sel_hi:[1,0]
	v_pk_add_f32 v[10:11], v[10:11], 1.0 op_sel_hi:[1,0]
	s_nop 0
	v_div_scale_f32 v13, s[0:1], v11, v11, v8
	v_rcp_f32_e32 v15, v13
	s_nop 0
	v_fma_f32 v16, -v13, v15, 1.0
	v_fmac_f32_e32 v15, v16, v15
	v_div_scale_f32 v16, vcc, v8, v11, v8
	v_mul_f32_e32 v17, v16, v15
	v_fma_f32 v18, -v13, v17, v16
	v_fmac_f32_e32 v17, v18, v15
	v_fma_f32 v13, -v13, v17, v16
	v_div_fmas_f32 v13, v13, v15, v17
	v_div_fixup_f32 v11, v13, v11, v8
	v_div_scale_f32 v8, s[0:1], v10, v10, v12
	v_rcp_f32_e32 v13, v8
	s_nop 0
	v_fma_f32 v15, -v8, v13, 1.0
	v_fmac_f32_e32 v13, v15, v13
	v_div_scale_f32 v15, vcc, v12, v10, v12
	v_mul_f32_e32 v16, v15, v13
	v_fma_f32 v17, -v8, v16, v15
	v_fmac_f32_e32 v16, v17, v13
	v_fma_f32 v8, -v8, v16, v15
	v_div_fmas_f32 v8, v8, v13, v16
	v_div_fixup_f32 v10, v8, v10, v12
	v_lshlrev_b32_e32 v12, 16, v9
	v_and_b32_e32 v13, 0xffff0000, v9
	v_pk_mul_f32 v[2:3], v[2:3], v[10:11]
	v_mul_f32_e32 v10, 0xbfb8aa3b, v12
	v_mul_f32_e32 v11, 0xbfb8aa3b, v13
	v_exp_f32_e32 v10, v10
	v_exp_f32_e32 v11, v11
	v_pk_mul_f32 v[8:9], v[58:59], v[4:5] op_sel_hi:[1,0]
	v_pk_add_f32 v[10:11], v[10:11], 1.0 op_sel_hi:[1,0]
	s_nop 0
	v_div_scale_f32 v15, s[0:1], v11, v11, v13
	v_rcp_f32_e32 v16, v15
	s_nop 0
	v_fma_f32 v17, -v15, v16, 1.0
	v_fmac_f32_e32 v16, v17, v16
	v_div_scale_f32 v17, vcc, v13, v11, v13
	v_mul_f32_e32 v18, v17, v16
	v_fma_f32 v19, -v15, v18, v17
	v_fmac_f32_e32 v18, v19, v16
	v_fma_f32 v15, -v15, v18, v17
	v_div_fmas_f32 v15, v15, v16, v18
	v_div_fixup_f32 v11, v15, v11, v13
	v_div_scale_f32 v13, s[0:1], v10, v10, v12
	v_rcp_f32_e32 v15, v13
	s_nop 0
	v_fma_f32 v16, -v13, v15, 1.0
	v_fmac_f32_e32 v15, v16, v15
	v_div_scale_f32 v16, vcc, v12, v10, v12
	v_mul_f32_e32 v17, v16, v15
	v_fma_f32 v18, -v13, v17, v16
	v_fmac_f32_e32 v17, v18, v15
	v_fma_f32 v13, -v13, v17, v16
	v_div_fmas_f32 v13, v13, v15, v17
	v_lshlrev_b32_e32 v15, 16, v5
	v_and_b32_e32 v5, 0xffff0000, v5
	v_div_fixup_f32 v10, v13, v10, v12
	v_mul_f32_e32 v12, 0xbfb8aa3b, v15
	v_mul_f32_e32 v13, 0xbfb8aa3b, v5
	v_exp_f32_e32 v12, v12
	v_exp_f32_e32 v13, v13
	v_pk_mul_f32 v[10:11], v[8:9], v[10:11]
	v_pk_mul_f32 v[8:9], v[60:61], v[4:5] op_sel_hi:[1,0]
	v_pk_add_f32 v[12:13], v[12:13], 1.0 op_sel_hi:[1,0]
	s_nop 0
	v_div_scale_f32 v16, s[0:1], v13, v13, v5
	v_rcp_f32_e32 v17, v16
	s_nop 0
	v_fma_f32 v18, -v16, v17, 1.0
	v_fmac_f32_e32 v17, v18, v17
	v_div_scale_f32 v18, vcc, v5, v13, v5
	v_mul_f32_e32 v19, v18, v17
	v_fma_f32 v20, -v16, v19, v18
	v_fmac_f32_e32 v19, v20, v17
	v_fma_f32 v16, -v16, v19, v18
	v_div_fmas_f32 v16, v16, v17, v19
	v_div_fixup_f32 v13, v16, v13, v5
	v_div_scale_f32 v5, s[0:1], v12, v12, v15
	v_rcp_f32_e32 v16, v5
	s_nop 0
	v_fma_f32 v17, -v5, v16, 1.0
	v_fmac_f32_e32 v16, v17, v16
	v_div_scale_f32 v17, vcc, v15, v12, v15
	v_mul_f32_e32 v18, v17, v16
	v_fma_f32 v19, -v5, v18, v17
	v_fmac_f32_e32 v18, v19, v16
	v_fma_f32 v5, -v5, v18, v17
	v_div_fmas_f32 v5, v5, v16, v18
	v_div_fixup_f32 v12, v5, v12, v15
	v_lshlrev_b32_e32 v5, 16, v14
	v_and_b32_e32 v16, 0xffff0000, v14
	v_mul_f32_e32 v14, 0xbfb8aa3b, v5
	v_mul_f32_e32 v15, 0xbfb8aa3b, v16
	v_exp_f32_e32 v14, v14
	v_exp_f32_e32 v15, v15
	v_pk_mul_f32 v[12:13], v[8:9], v[12:13]
	v_pk_mul_f32 v[8:9], v[62:63], v[4:5] op_sel_hi:[1,0]
	v_pk_add_f32 v[14:15], v[14:15], 1.0 op_sel_hi:[1,0]
	s_nop 0
	v_div_scale_f32 v17, s[0:1], v15, v15, v16
	v_rcp_f32_e32 v18, v17
	s_nop 0
	v_fma_f32 v19, -v17, v18, 1.0
	v_fmac_f32_e32 v18, v19, v18
	v_div_scale_f32 v19, vcc, v16, v15, v16
	v_mul_f32_e32 v20, v19, v18
	v_fma_f32 v21, -v17, v20, v19
	v_fmac_f32_e32 v20, v21, v18
	v_fma_f32 v17, -v17, v20, v19
	v_div_fmas_f32 v17, v17, v18, v20
	v_div_fixup_f32 v15, v17, v15, v16
	v_div_scale_f32 v16, s[0:1], v14, v14, v5
	v_rcp_f32_e32 v17, v16
	s_nop 0
	v_fma_f32 v18, -v16, v17, 1.0
	v_fmac_f32_e32 v17, v18, v17
	v_div_scale_f32 v18, vcc, v5, v14, v5
	v_mul_f32_e32 v19, v18, v17
	v_fma_f32 v20, -v16, v19, v18
	v_fmac_f32_e32 v19, v20, v17
	v_fma_f32 v16, -v16, v19, v18
	v_div_fmas_f32 v16, v16, v17, v19
	v_div_fixup_f32 v14, v16, v14, v5
	v_pk_mul_f32 v[14:15], v[8:9], v[14:15]
	v_cvt_pk_bf16_f32 v8, v2, v3
	v_cvt_pk_bf16_f32 v9, v10, v11
	v_cvt_pk_bf16_f32 v10, v12, v13
	v_cvt_pk_bf16_f32 v11, v14, v15
	s_nop 0
	v_permlane32_swap_b32_e32 v8, v10
	v_permlane32_swap_b32_e32 v9, v11
	global_store_dwordx4 v[6:7], v[8:11], off offset:32
	s_waitcnt vmcnt(3)
	v_mov_b32_e32 v5, v70
	s_nop 1
	v_mov_b32_e32 v8, v68
	s_nop 1
	v_permlane32_swap_b32_e32 v8, v5
	v_lshlrev_b32_e32 v12, 16, v8
	v_and_b32_e32 v8, 0xffff0000, v8
	v_mov_b32_e32 v14, v71
	v_mul_f32_e32 v10, 0xbfb8aa3b, v12
	v_mul_f32_e32 v11, 0xbfb8aa3b, v8
	v_exp_f32_e32 v10, v10
	v_exp_f32_e32 v11, v11
	v_mov_b32_e32 v9, v69
	s_nop 1
	v_permlane32_swap_b32_e32 v9, v14
	v_pk_mul_f32 v[2:3], v[32:33], v[4:5] op_sel_hi:[1,0]
	v_pk_add_f32 v[10:11], v[10:11], 1.0 op_sel_hi:[1,0]
	s_nop 0
	v_div_scale_f32 v13, s[0:1], v11, v11, v8
	v_rcp_f32_e32 v15, v13
	s_nop 0
	v_fma_f32 v16, -v13, v15, 1.0
	v_fmac_f32_e32 v15, v16, v15
	v_div_scale_f32 v16, vcc, v8, v11, v8
	v_mul_f32_e32 v17, v16, v15
	v_fma_f32 v18, -v13, v17, v16
	v_fmac_f32_e32 v17, v18, v15
	v_fma_f32 v13, -v13, v17, v16
	v_div_fmas_f32 v13, v13, v15, v17
	v_div_fixup_f32 v11, v13, v11, v8
	v_div_scale_f32 v8, s[0:1], v10, v10, v12
	v_rcp_f32_e32 v13, v8
	s_nop 0
	v_fma_f32 v15, -v8, v13, 1.0
	v_fmac_f32_e32 v13, v15, v13
	v_div_scale_f32 v15, vcc, v12, v10, v12
	v_mul_f32_e32 v16, v15, v13
	v_fma_f32 v17, -v8, v16, v15
	v_fmac_f32_e32 v16, v17, v13
	v_fma_f32 v8, -v8, v16, v15
	v_div_fmas_f32 v8, v8, v13, v16
	v_div_fixup_f32 v10, v8, v10, v12
	v_lshlrev_b32_e32 v12, 16, v9
	v_and_b32_e32 v13, 0xffff0000, v9
	v_pk_mul_f32 v[2:3], v[2:3], v[10:11]
	v_mul_f32_e32 v10, 0xbfb8aa3b, v12
	v_mul_f32_e32 v11, 0xbfb8aa3b, v13
	v_exp_f32_e32 v10, v10
	v_exp_f32_e32 v11, v11
	v_pk_mul_f32 v[8:9], v[34:35], v[4:5] op_sel_hi:[1,0]
	v_pk_add_f32 v[10:11], v[10:11], 1.0 op_sel_hi:[1,0]
	s_nop 0
	v_div_scale_f32 v15, s[0:1], v11, v11, v13
	v_rcp_f32_e32 v16, v15
	s_nop 0
	v_fma_f32 v17, -v15, v16, 1.0
	v_fmac_f32_e32 v16, v17, v16
	v_div_scale_f32 v17, vcc, v13, v11, v13
	v_mul_f32_e32 v18, v17, v16
	v_fma_f32 v19, -v15, v18, v17
	v_fmac_f32_e32 v18, v19, v16
	v_fma_f32 v15, -v15, v18, v17
	v_div_fmas_f32 v15, v15, v16, v18
	v_div_fixup_f32 v11, v15, v11, v13
	v_div_scale_f32 v13, s[0:1], v10, v10, v12
	v_rcp_f32_e32 v15, v13
	s_nop 0
	v_fma_f32 v16, -v13, v15, 1.0
	v_fmac_f32_e32 v15, v16, v15
	v_div_scale_f32 v16, vcc, v12, v10, v12
	v_mul_f32_e32 v17, v16, v15
	v_fma_f32 v18, -v13, v17, v16
	v_fmac_f32_e32 v17, v18, v15
	v_fma_f32 v13, -v13, v17, v16
	v_div_fmas_f32 v13, v13, v15, v17
	v_lshlrev_b32_e32 v15, 16, v5
	v_and_b32_e32 v5, 0xffff0000, v5
	v_div_fixup_f32 v10, v13, v10, v12
	v_mul_f32_e32 v12, 0xbfb8aa3b, v15
	v_mul_f32_e32 v13, 0xbfb8aa3b, v5
	v_exp_f32_e32 v12, v12
	v_exp_f32_e32 v13, v13
	v_pk_mul_f32 v[10:11], v[8:9], v[10:11]
	v_pk_mul_f32 v[8:9], v[36:37], v[4:5] op_sel_hi:[1,0]
	v_pk_add_f32 v[12:13], v[12:13], 1.0 op_sel_hi:[1,0]
	s_nop 0
	v_div_scale_f32 v16, s[0:1], v13, v13, v5
	v_rcp_f32_e32 v17, v16
	s_nop 0
	v_fma_f32 v18, -v16, v17, 1.0
	v_fmac_f32_e32 v17, v18, v17
	v_div_scale_f32 v18, vcc, v5, v13, v5
	v_mul_f32_e32 v19, v18, v17
	v_fma_f32 v20, -v16, v19, v18
	v_fmac_f32_e32 v19, v20, v17
	v_fma_f32 v16, -v16, v19, v18
	v_div_fmas_f32 v16, v16, v17, v19
	v_div_fixup_f32 v13, v16, v13, v5
	v_div_scale_f32 v5, s[0:1], v12, v12, v15
	v_rcp_f32_e32 v16, v5
	s_nop 0
	v_fma_f32 v17, -v5, v16, 1.0
	v_fmac_f32_e32 v16, v17, v16
	v_div_scale_f32 v17, vcc, v15, v12, v15
	v_mul_f32_e32 v18, v17, v16
	v_fma_f32 v19, -v5, v18, v17
	v_fmac_f32_e32 v18, v19, v16
	v_fma_f32 v5, -v5, v18, v17
	v_div_fmas_f32 v5, v5, v16, v18
	v_div_fixup_f32 v12, v5, v12, v15
	v_lshlrev_b32_e32 v5, 16, v14
	v_and_b32_e32 v16, 0xffff0000, v14
	v_mul_f32_e32 v14, 0xbfb8aa3b, v5
	v_mul_f32_e32 v15, 0xbfb8aa3b, v16
	v_exp_f32_e32 v14, v14
	v_exp_f32_e32 v15, v15
	v_pk_mul_f32 v[12:13], v[8:9], v[12:13]
	v_pk_mul_f32 v[8:9], v[38:39], v[4:5] op_sel_hi:[1,0]
	v_pk_add_f32 v[14:15], v[14:15], 1.0 op_sel_hi:[1,0]
	s_nop 0
	v_div_scale_f32 v17, s[0:1], v15, v15, v16
	v_rcp_f32_e32 v18, v17
	s_nop 0
	v_fma_f32 v19, -v17, v18, 1.0
	v_fmac_f32_e32 v18, v19, v18
	v_div_scale_f32 v19, vcc, v16, v15, v16
	v_mul_f32_e32 v20, v19, v18
	v_fma_f32 v21, -v17, v20, v19
	v_fmac_f32_e32 v20, v21, v18
	v_fma_f32 v17, -v17, v20, v19
	v_div_fmas_f32 v17, v17, v18, v20
	v_div_fixup_f32 v15, v17, v15, v16
	v_div_scale_f32 v16, s[0:1], v14, v14, v5
	v_rcp_f32_e32 v17, v16
	s_nop 0
	v_fma_f32 v18, -v16, v17, 1.0
	v_fmac_f32_e32 v17, v18, v17
	v_div_scale_f32 v18, vcc, v5, v14, v5
	v_mul_f32_e32 v19, v18, v17
	v_fma_f32 v20, -v16, v19, v18
	v_fmac_f32_e32 v19, v20, v17
	v_fma_f32 v16, -v16, v19, v18
	v_div_fmas_f32 v16, v16, v17, v19
	v_div_fixup_f32 v14, v16, v14, v5
	v_pk_mul_f32 v[14:15], v[8:9], v[14:15]
	v_cvt_pk_bf16_f32 v8, v2, v3
	v_cvt_pk_bf16_f32 v9, v10, v11
	v_cvt_pk_bf16_f32 v10, v12, v13
	v_cvt_pk_bf16_f32 v11, v14, v15
	s_nop 0
	v_permlane32_swap_b32_e32 v8, v10
	v_permlane32_swap_b32_e32 v9, v11
	global_store_dwordx4 v[6:7], v[8:11], off offset:64
	s_waitcnt vmcnt(3)
	v_mov_b32_e32 v5, v74
	s_nop 1
	v_mov_b32_e32 v0, v72
	s_nop 1
	v_permlane32_swap_b32_e32 v0, v5
	v_lshlrev_b32_e32 v10, 16, v0
	v_and_b32_e32 v0, 0xffff0000, v0
	v_mul_f32_e32 v8, 0xbfb8aa3b, v10
	v_mul_f32_e32 v9, 0xbfb8aa3b, v0
	v_exp_f32_e32 v8, v8
	v_exp_f32_e32 v9, v9
	v_mov_b32_e32 v12, v75
	s_nop 1
	v_mov_b32_e32 v1, v73
	s_nop 1
	v_permlane32_swap_b32_e32 v1, v12
	v_pk_add_f32 v[8:9], v[8:9], 1.0 op_sel_hi:[1,0]
	v_pk_mul_f32 v[2:3], v[40:41], v[4:5] op_sel_hi:[1,0]
	v_div_scale_f32 v11, s[0:1], v9, v9, v0
	v_rcp_f32_e32 v13, v11
	s_nop 0
	v_fma_f32 v14, -v11, v13, 1.0
	v_fmac_f32_e32 v13, v14, v13
	v_div_scale_f32 v14, vcc, v0, v9, v0
	v_mul_f32_e32 v15, v14, v13
	v_fma_f32 v16, -v11, v15, v14
	v_fmac_f32_e32 v15, v16, v13
	v_fma_f32 v11, -v11, v15, v14
	v_div_fmas_f32 v11, v11, v13, v15
	v_div_fixup_f32 v9, v11, v9, v0
	v_div_scale_f32 v0, s[0:1], v8, v8, v10
	v_rcp_f32_e32 v11, v0
	s_nop 0
	v_fma_f32 v13, -v0, v11, 1.0
	v_fmac_f32_e32 v11, v13, v11
	v_div_scale_f32 v13, vcc, v10, v8, v10
	v_mul_f32_e32 v14, v13, v11
	v_fma_f32 v15, -v0, v14, v13
	v_fmac_f32_e32 v14, v15, v11
	v_fma_f32 v0, -v0, v14, v13
	v_div_fmas_f32 v0, v0, v11, v14
	v_div_fixup_f32 v8, v0, v8, v10
	v_lshlrev_b32_e32 v10, 16, v1
	v_and_b32_e32 v11, 0xffff0000, v1
	v_pk_mul_f32 v[2:3], v[2:3], v[8:9]
	v_mul_f32_e32 v8, 0xbfb8aa3b, v10
	v_mul_f32_e32 v9, 0xbfb8aa3b, v11
	v_exp_f32_e32 v8, v8
	v_exp_f32_e32 v9, v9
	v_pk_mul_f32 v[0:1], v[42:43], v[4:5] op_sel_hi:[1,0]
	v_pk_add_f32 v[8:9], v[8:9], 1.0 op_sel_hi:[1,0]
	s_nop 0
	v_div_scale_f32 v13, s[0:1], v9, v9, v11
	v_rcp_f32_e32 v14, v13
	s_nop 0
	v_fma_f32 v15, -v13, v14, 1.0
	v_fmac_f32_e32 v14, v15, v14
	v_div_scale_f32 v15, vcc, v11, v9, v11
	v_mul_f32_e32 v16, v15, v14
	v_fma_f32 v17, -v13, v16, v15
	v_fmac_f32_e32 v16, v17, v14
	v_fma_f32 v13, -v13, v16, v15
	v_div_fmas_f32 v13, v13, v14, v16
	v_div_fixup_f32 v9, v13, v9, v11
	v_div_scale_f32 v11, s[0:1], v8, v8, v10
	v_rcp_f32_e32 v13, v11
	s_nop 0
	v_fma_f32 v14, -v11, v13, 1.0
	v_fmac_f32_e32 v13, v14, v13
	v_div_scale_f32 v14, vcc, v10, v8, v10
	v_mul_f32_e32 v15, v14, v13
	v_fma_f32 v16, -v11, v15, v14
	v_fmac_f32_e32 v15, v16, v13
	v_fma_f32 v11, -v11, v15, v14
	v_div_fmas_f32 v11, v11, v13, v15
	v_lshlrev_b32_e32 v13, 16, v5
	v_and_b32_e32 v5, 0xffff0000, v5
	v_div_fixup_f32 v8, v11, v8, v10
	v_mul_f32_e32 v10, 0xbfb8aa3b, v13
	v_mul_f32_e32 v11, 0xbfb8aa3b, v5
	v_exp_f32_e32 v10, v10
	v_exp_f32_e32 v11, v11
	v_pk_mul_f32 v[8:9], v[0:1], v[8:9]
	v_pk_mul_f32 v[0:1], v[44:45], v[4:5] op_sel_hi:[1,0]
	v_pk_add_f32 v[10:11], v[10:11], 1.0 op_sel_hi:[1,0]
	s_nop 0
	v_div_scale_f32 v14, s[0:1], v11, v11, v5
	v_rcp_f32_e32 v15, v14
	s_nop 0
	v_fma_f32 v16, -v14, v15, 1.0
	v_fmac_f32_e32 v15, v16, v15
	v_div_scale_f32 v16, vcc, v5, v11, v5
	v_mul_f32_e32 v17, v16, v15
	v_fma_f32 v18, -v14, v17, v16
	v_fmac_f32_e32 v17, v18, v15
	v_fma_f32 v14, -v14, v17, v16
	v_div_fmas_f32 v14, v14, v15, v17
	v_div_fixup_f32 v11, v14, v11, v5
	v_div_scale_f32 v5, s[0:1], v10, v10, v13
	v_rcp_f32_e32 v14, v5
	s_nop 0
	v_fma_f32 v15, -v5, v14, 1.0
	v_fmac_f32_e32 v14, v15, v14
	v_div_scale_f32 v15, vcc, v13, v10, v13
	v_mul_f32_e32 v16, v15, v14
	v_fma_f32 v17, -v5, v16, v15
	v_fmac_f32_e32 v16, v17, v14
	v_fma_f32 v5, -v5, v16, v15
	v_div_fmas_f32 v5, v5, v14, v16
	v_div_fixup_f32 v10, v5, v10, v13
	v_lshlrev_b32_e32 v13, 16, v12
	v_and_b32_e32 v12, 0xffff0000, v12
	v_pk_mul_f32 v[10:11], v[0:1], v[10:11]
	v_pk_mul_f32 v[0:1], v[46:47], v[4:5] op_sel_hi:[1,0]
	v_mul_f32_e32 v4, 0xbfb8aa3b, v13
	v_mul_f32_e32 v5, 0xbfb8aa3b, v12
	v_exp_f32_e32 v4, v4
	v_exp_f32_e32 v5, v5
	s_nop 0
	v_pk_add_f32 v[4:5], v[4:5], 1.0 op_sel_hi:[1,0]
	s_nop 0
	v_div_scale_f32 v14, s[0:1], v5, v5, v12
	v_rcp_f32_e32 v15, v14
	s_nop 0
	v_fma_f32 v16, -v14, v15, 1.0
	v_fmac_f32_e32 v15, v16, v15
	v_div_scale_f32 v16, vcc, v12, v5, v12
	v_mul_f32_e32 v17, v16, v15
	v_fma_f32 v18, -v14, v17, v16
	v_fmac_f32_e32 v17, v18, v15
	v_fma_f32 v14, -v14, v17, v16
	v_div_fmas_f32 v14, v14, v15, v17
	v_div_fixup_f32 v5, v14, v5, v12
	v_div_scale_f32 v12, s[0:1], v4, v4, v13
	v_rcp_f32_e32 v14, v12
	s_nop 0
	v_fma_f32 v15, -v12, v14, 1.0
	v_fmac_f32_e32 v14, v15, v14
	v_div_scale_f32 v15, vcc, v13, v4, v13
	v_mul_f32_e32 v16, v15, v14
	v_fma_f32 v17, -v12, v16, v15
	v_fmac_f32_e32 v16, v17, v14
	v_fma_f32 v12, -v12, v16, v15
	v_div_fmas_f32 v12, v12, v14, v16
	v_div_fixup_f32 v4, v12, v4, v13
	v_pk_mul_f32 v[4:5], v[0:1], v[4:5]
	v_cvt_pk_bf16_f32 v0, v2, v3
	v_cvt_pk_bf16_f32 v1, v8, v9
	v_cvt_pk_bf16_f32 v2, v10, v11
	v_cvt_pk_bf16_f32 v3, v4, v5
	s_nop 0
	v_permlane32_swap_b32_e32 v0, v2
	v_permlane32_swap_b32_e32 v1, v3
	global_store_dwordx4 v[6:7], v[0:3], off offset:96
	s_branch .LBB0_476

.LBB0_475:
	v_lshlrev_b32_e32 v0, 16, v199
	v_mul_f32_e32 v0, 0xbfb8aa3b, v0
	v_exp_f32_e32 v0, v0
	v_lshlrev_b64 v[10:11], 11, v[200:201]
	v_lshlrev_b32_e32 v192, 1, v235
	v_readlane_b32 s10, v254, 51
	v_add_f32_e32 v0, 1.0, v0
	v_div_scale_f32 v1, s[0:1], v0, v0, 1.0
	v_rcp_f32_e32 v2, v1
	s_nop 0
	v_fma_f32 v3, -v1, v2, 1.0
	v_fmac_f32_e32 v2, v3, v2
	v_div_scale_f32 v3, vcc, 1.0, v0, 1.0
	v_mul_f32_e32 v4, v3, v2
	v_fma_f32 v5, -v1, v4, v3
	v_fmac_f32_e32 v4, v5, v2
	v_fma_f32 v1, -v1, v4, v3
	v_div_fmas_f32 v1, v1, v2, v4
	v_div_fixup_f32 v4, v1, v0, 1.0
	v_and_b32_e32 v0, 0xffff0000, v199
	v_mul_f32_e32 v0, 0xbfb8aa3b, v0
	v_exp_f32_e32 v206, v0
	s_waitcnt lgkmcnt(0)
	v_pk_add_f32 v[0:1], v[206:207], v[194:195]
	s_nop 0
	v_div_scale_f32 v2, s[0:1], v0, v0, 1.0
	v_rcp_f32_e32 v3, v2
	ds_bpermute_b32 v195, v236, v209
	v_fma_f32 v5, -v2, v3, 1.0
	v_fmac_f32_e32 v3, v5, v3
	v_div_scale_f32 v5, vcc, 1.0, v0, 1.0
	v_mul_f32_e32 v6, v5, v3
	v_fma_f32 v7, -v2, v6, v5
	v_fmac_f32_e32 v6, v7, v3
	v_fma_f32 v2, -v2, v6, v5
	v_div_fmas_f32 v2, v2, v3, v6
	v_div_fixup_f32 v0, v2, v0, 1.0
	v_div_scale_f32 v2, s[0:1], v1, v1, v0
	v_rcp_f32_e32 v3, v2
	s_nop 0
	v_fma_f32 v5, -v2, v3, 1.0
	v_fmac_f32_e32 v3, v5, v3
	v_div_scale_f32 v5, vcc, v0, v1, v0
	v_mul_f32_e32 v6, v5, v3
	v_fma_f32 v7, -v2, v6, v5
	v_fmac_f32_e32 v6, v7, v3
	v_fma_f32 v2, -v2, v6, v5
	v_div_fmas_f32 v2, v2, v3, v6
	v_div_fixup_f32 v6, v2, v1, v0
	v_lshlrev_b32_e32 v0, 16, v197
	v_mul_f32_e32 v0, 0xbfb8aa3b, v0
	v_exp_f32_e32 v208, v0
	s_waitcnt lgkmcnt(0)
	v_pk_add_f32 v[0:1], v[208:209], v[194:195]
	s_nop 0
	v_div_scale_f32 v2, s[0:1], v0, v0, 1.0
	v_rcp_f32_e32 v3, v2
	s_nop 0
	v_fma_f32 v5, -v2, v3, 1.0
	v_fmac_f32_e32 v3, v5, v3
	v_div_scale_f32 v5, vcc, 1.0, v0, 1.0
	v_mul_f32_e32 v7, v5, v3
	v_fma_f32 v8, -v2, v7, v5
	v_fmac_f32_e32 v7, v8, v3
	v_fma_f32 v2, -v2, v7, v5
	v_div_fmas_f32 v2, v2, v3, v7
	v_div_fixup_f32 v0, v2, v0, 1.0
	v_div_scale_f32 v2, s[0:1], v1, v1, v0
	v_rcp_f32_e32 v3, v2
	v_readlane_b32 s0, v254, 43
	v_readlane_b32 s1, v254, 44
	v_fma_f32 v5, -v2, v3, 1.0
	v_fmac_f32_e32 v3, v5, v3
	v_div_scale_f32 v5, vcc, v0, v1, v0
	v_mul_f32_e32 v7, v5, v3
	v_fma_f32 v8, -v2, v7, v5
	v_fmac_f32_e32 v7, v8, v3
	v_fma_f32 v2, -v2, v7, v5
	v_div_fmas_f32 v2, v2, v3, v7
	v_div_fixup_f32 v8, v2, v1, v0
	v_lshlrev_b64 v[0:1], 1, v[204:205]
	v_lshl_add_u64 v[2:3], v[202:203], 0, v[0:1]
	v_lshl_add_u64 v[10:11], s[0:1], 0, v[10:11]
	v_lshl_add_u64 v[10:11], v[10:11], 0, v[0:1]
	v_lshl_add_u64 v[2:3], v[2:3], 0, v[192:193]
	s_mov_b64 s[0:1], 0x1200
	v_lshl_add_u64 v[0:1], v[2:3], 0, s[0:1]
	v_lshl_add_u64 v[16:17], v[10:11], 0, v[192:193]
	s_mov_b64 s[0:1], 0xd210400
	v_lshl_add_u64 v[10:11], v[16:17], 0, s[0:1]
	s_movk_i32 s0, 0x1000
	v_add_co_u32_e32 v2, vcc, s0, v2
	s_nop 1
	v_addc_co_u32_e32 v3, vcc, 0, v3, vcc
	global_load_dwordx4 v[12:15], v[2:3], off offset:512
	global_load_dwordx4 v[128:131], v[0:1], off offset:32
	global_load_dwordx4 v[132:135], v[0:1], off offset:64
	global_load_dwordx4 v[136:139], v[0:1], off offset:96
	s_waitcnt vmcnt(3)
	v_mov_b32_e32 v5, v14
	s_nop 1
	v_permlane32_swap_b32_e32 v12, v5
	v_lshlrev_b32_e32 v9, 16, v12
	v_and_b32_e32 v12, 0xffff0000, v12
	v_mov_b32_e32 v7, v15
	v_mul_f32_e32 v14, 0xbfb8aa3b, v9
	v_mul_f32_e32 v15, 0xbfb8aa3b, v12
	v_exp_f32_e32 v14, v14
	v_exp_f32_e32 v15, v15
	v_permlane32_swap_b32_e32 v13, v7
	v_pk_mul_f32 v[2:3], v[96:97], v[6:7] op_sel_hi:[1,0]
	v_pk_add_f32 v[14:15], v[14:15], 1.0 op_sel_hi:[1,0]
	v_pk_fma_f32 v[2:3], v[4:5], v[80:81], v[2:3] op_sel_hi:[0,1,1]
	v_div_scale_f32 v18, s[0:1], v15, v15, v12
	v_rcp_f32_e32 v19, v18
	v_pk_fma_f32 v[2:3], v[112:113], v[8:9], v[2:3] op_sel_hi:[1,0,1]
	v_fma_f32 v20, -v18, v19, 1.0
	v_fmac_f32_e32 v19, v20, v19
	v_div_scale_f32 v20, vcc, v12, v15, v12
	v_mul_f32_e32 v21, v20, v19
	v_fma_f32 v22, -v18, v21, v20
	v_fmac_f32_e32 v21, v22, v19
	v_fma_f32 v18, -v18, v21, v20
	v_div_fmas_f32 v18, v18, v19, v21
	v_div_fixup_f32 v15, v18, v15, v12
	v_div_scale_f32 v12, s[0:1], v14, v14, v9
	v_rcp_f32_e32 v18, v12
	s_nop 0
	v_fma_f32 v19, -v12, v18, 1.0
	v_fmac_f32_e32 v18, v19, v18
	v_div_scale_f32 v19, vcc, v9, v14, v9
	v_mul_f32_e32 v20, v19, v18
	v_fma_f32 v21, -v12, v20, v19
	v_fmac_f32_e32 v20, v21, v18
	v_fma_f32 v12, -v12, v20, v19
	v_div_fmas_f32 v12, v12, v18, v20
	v_div_fixup_f32 v14, v12, v14, v9
	v_lshlrev_b32_e32 v9, 16, v13
	v_and_b32_e32 v18, 0xffff0000, v13
	v_pk_mul_f32 v[2:3], v[2:3], v[14:15]
	v_mul_f32_e32 v14, 0xbfb8aa3b, v9
	v_mul_f32_e32 v15, 0xbfb8aa3b, v18
	v_exp_f32_e32 v14, v14
	v_exp_f32_e32 v15, v15
	v_pk_mul_f32 v[12:13], v[98:99], v[6:7] op_sel_hi:[1,0]
	v_pk_add_f32 v[14:15], v[14:15], 1.0 op_sel_hi:[1,0]
	s_nop 0
	v_div_scale_f32 v19, s[0:1], v15, v15, v18
	v_rcp_f32_e32 v20, v19
	v_pk_fma_f32 v[12:13], v[4:5], v[82:83], v[12:13] op_sel_hi:[0,1,1]
	v_pk_fma_f32 v[12:13], v[114:115], v[8:9], v[12:13] op_sel_hi:[1,0,1]
	v_fma_f32 v21, -v19, v20, 1.0
	v_fmac_f32_e32 v20, v21, v20
	v_div_scale_f32 v21, vcc, v18, v15, v18
	v_mul_f32_e32 v22, v21, v20
	v_fma_f32 v23, -v19, v22, v21
	v_fmac_f32_e32 v22, v23, v20
	v_fma_f32 v19, -v19, v22, v21
	v_div_fmas_f32 v19, v19, v20, v22
	v_div_fixup_f32 v15, v19, v15, v18
	v_div_scale_f32 v18, s[0:1], v14, v14, v9
	v_rcp_f32_e32 v19, v18
	s_nop 0
	v_fma_f32 v20, -v18, v19, 1.0
	v_fmac_f32_e32 v19, v20, v19
	v_div_scale_f32 v20, vcc, v9, v14, v9
	v_mul_f32_e32 v21, v20, v19
	v_fma_f32 v22, -v18, v21, v20
	v_fmac_f32_e32 v21, v22, v19
	v_fma_f32 v18, -v18, v21, v20
	v_div_fmas_f32 v18, v18, v19, v21
	v_div_fixup_f32 v14, v18, v14, v9
	v_lshlrev_b32_e32 v9, 16, v5
	v_and_b32_e32 v5, 0xffff0000, v5
	v_mul_f32_e32 v18, 0xbfb8aa3b, v9
	v_mul_f32_e32 v19, 0xbfb8aa3b, v5
	v_exp_f32_e32 v18, v18
	v_exp_f32_e32 v19, v19
	v_pk_mul_f32 v[14:15], v[12:13], v[14:15]
	v_pk_mul_f32 v[12:13], v[100:101], v[6:7] op_sel_hi:[1,0]
	v_pk_add_f32 v[18:19], v[18:19], 1.0 op_sel_hi:[1,0]
	s_nop 0
	v_div_scale_f32 v20, s[0:1], v19, v19, v5
	v_rcp_f32_e32 v21, v20
	v_pk_fma_f32 v[12:13], v[4:5], v[84:85], v[12:13] op_sel_hi:[0,1,1]
	v_pk_fma_f32 v[12:13], v[116:117], v[8:9], v[12:13] op_sel_hi:[1,0,1]
	v_fma_f32 v22, -v20, v21, 1.0
	v_fmac_f32_e32 v21, v22, v21
	v_div_scale_f32 v22, vcc, v5, v19, v5
	v_mul_f32_e32 v23, v22, v21
	v_fma_f32 v24, -v20, v23, v22
	v_fmac_f32_e32 v23, v24, v21
	v_fma_f32 v20, -v20, v23, v22
	v_div_fmas_f32 v20, v20, v21, v23
	v_div_fixup_f32 v19, v20, v19, v5
	v_div_scale_f32 v5, s[0:1], v18, v18, v9
	v_rcp_f32_e32 v20, v5
	s_nop 0
	v_fma_f32 v21, -v5, v20, 1.0
	v_fmac_f32_e32 v20, v21, v20
	v_div_scale_f32 v21, vcc, v9, v18, v9
	v_mul_f32_e32 v22, v21, v20
	v_fma_f32 v23, -v5, v22, v21
	v_fmac_f32_e32 v22, v23, v20
	v_fma_f32 v5, -v5, v22, v21
	v_div_fmas_f32 v5, v5, v20, v22
	v_div_fixup_f32 v18, v5, v18, v9
	v_lshlrev_b32_e32 v5, 16, v7
	v_and_b32_e32 v7, 0xffff0000, v7
	v_pk_mul_f32 v[18:19], v[12:13], v[18:19]
	v_pk_mul_f32 v[12:13], v[102:103], v[6:7] op_sel_hi:[1,0]
	s_nop 0
	v_pk_fma_f32 v[12:13], v[4:5], v[86:87], v[12:13] op_sel_hi:[0,1,1]
	v_pk_fma_f32 v[12:13], v[118:119], v[8:9], v[12:13] op_sel_hi:[1,0,1]
	v_mul_f32_e32 v9, 0xbfb8aa3b, v5
	v_exp_f32_e32 v20, v9
	v_mul_f32_e32 v9, 0xbfb8aa3b, v7
	v_exp_f32_e32 v21, v9
	s_nop 0
	v_pk_add_f32 v[20:21], v[20:21], 1.0 op_sel_hi:[1,0]
	s_nop 0
	v_div_scale_f32 v9, s[0:1], v21, v21, v7
	v_rcp_f32_e32 v22, v9
	s_nop 0
	v_fma_f32 v23, -v9, v22, 1.0
	v_fmac_f32_e32 v22, v23, v22
	v_div_scale_f32 v23, vcc, v7, v21, v7
	v_mul_f32_e32 v24, v23, v22
	v_fma_f32 v25, -v9, v24, v23
	v_fmac_f32_e32 v24, v25, v22
	v_fma_f32 v9, -v9, v24, v23
	v_div_fmas_f32 v9, v9, v22, v24
	v_div_fixup_f32 v21, v9, v21, v7
	v_div_scale_f32 v7, s[0:1], v20, v20, v5
	v_rcp_f32_e32 v9, v7
	s_mov_b32 s0, 0xd210000
	v_fma_f32 v22, -v7, v9, 1.0
	v_fmac_f32_e32 v9, v22, v9
	v_div_scale_f32 v22, vcc, v5, v20, v5
	v_mul_f32_e32 v23, v22, v9
	v_fma_f32 v24, -v7, v23, v22
	v_fmac_f32_e32 v23, v24, v9
	v_fma_f32 v7, -v7, v23, v22
	v_div_fmas_f32 v7, v7, v9, v23
	v_div_fixup_f32 v20, v7, v20, v5
	v_pk_mul_f32 v[20:21], v[12:13], v[20:21]
	v_cvt_pk_bf16_f32 v12, v2, v3
	v_cvt_pk_bf16_f32 v13, v14, v15
	v_cvt_pk_bf16_f32 v14, v18, v19
	v_cvt_pk_bf16_f32 v15, v20, v21
	v_add_co_u32_e32 v2, vcc, s0, v16
	v_permlane32_swap_b32_e32 v12, v14
	v_permlane32_swap_b32_e32 v13, v15
	v_addc_co_u32_e32 v3, vcc, 0, v17, vcc
	global_store_dwordx4 v[2:3], v[12:15], off offset:1024
	s_waitcnt vmcnt(3)
	v_mov_b32_e32 v5, v130
	s_nop 1
	v_mov_b32_e32 v12, v128
	s_nop 1
	v_permlane32_swap_b32_e32 v12, v5
	v_lshlrev_b32_e32 v9, 16, v12
	v_and_b32_e32 v12, 0xffff0000, v12
	v_mov_b32_e32 v7, v131
	v_mul_f32_e32 v14, 0xbfb8aa3b, v9
	v_mul_f32_e32 v15, 0xbfb8aa3b, v12
	v_exp_f32_e32 v14, v14
	v_exp_f32_e32 v15, v15
	v_mov_b32_e32 v13, v129
	s_nop 1
	v_permlane32_swap_b32_e32 v13, v7
	v_pk_mul_f32 v[2:3], v[104:105], v[6:7] op_sel_hi:[1,0]
	v_pk_add_f32 v[14:15], v[14:15], 1.0 op_sel_hi:[1,0]
	v_pk_fma_f32 v[2:3], v[4:5], v[88:89], v[2:3] op_sel_hi:[0,1,1]
	v_div_scale_f32 v16, s[0:1], v15, v15, v12
	v_rcp_f32_e32 v17, v16
	v_pk_fma_f32 v[2:3], v[120:121], v[8:9], v[2:3] op_sel_hi:[1,0,1]
	v_fma_f32 v18, -v16, v17, 1.0
	v_fmac_f32_e32 v17, v18, v17
	v_div_scale_f32 v18, vcc, v12, v15, v12
	v_mul_f32_e32 v19, v18, v17
	v_fma_f32 v20, -v16, v19, v18
	v_fmac_f32_e32 v19, v20, v17
	v_fma_f32 v16, -v16, v19, v18
	v_div_fmas_f32 v16, v16, v17, v19
	v_div_fixup_f32 v15, v16, v15, v12
	v_div_scale_f32 v12, s[0:1], v14, v14, v9
	v_rcp_f32_e32 v16, v12
	s_nop 0
	v_fma_f32 v17, -v12, v16, 1.0
	v_fmac_f32_e32 v16, v17, v16
	v_div_scale_f32 v17, vcc, v9, v14, v9
	v_mul_f32_e32 v18, v17, v16
	v_fma_f32 v19, -v12, v18, v17
	v_fmac_f32_e32 v18, v19, v16
	v_fma_f32 v12, -v12, v18, v17
	v_div_fmas_f32 v12, v12, v16, v18
	v_div_fixup_f32 v14, v12, v14, v9
	v_lshlrev_b32_e32 v9, 16, v13
	v_and_b32_e32 v16, 0xffff0000, v13
	v_pk_mul_f32 v[2:3], v[2:3], v[14:15]
	v_mul_f32_e32 v14, 0xbfb8aa3b, v9
	v_mul_f32_e32 v15, 0xbfb8aa3b, v16
	v_exp_f32_e32 v14, v14
	v_exp_f32_e32 v15, v15
	v_pk_mul_f32 v[12:13], v[106:107], v[6:7] op_sel_hi:[1,0]
	v_pk_add_f32 v[14:15], v[14:15], 1.0 op_sel_hi:[1,0]
	s_nop 0
	v_div_scale_f32 v17, s[0:1], v15, v15, v16
	v_rcp_f32_e32 v18, v17
	v_pk_fma_f32 v[12:13], v[4:5], v[90:91], v[12:13] op_sel_hi:[0,1,1]
	v_pk_fma_f32 v[12:13], v[122:123], v[8:9], v[12:13] op_sel_hi:[1,0,1]
	v_fma_f32 v19, -v17, v18, 1.0
	v_fmac_f32_e32 v18, v19, v18
	v_div_scale_f32 v19, vcc, v16, v15, v16
	v_mul_f32_e32 v20, v19, v18
	v_fma_f32 v21, -v17, v20, v19
	v_fmac_f32_e32 v20, v21, v18
	v_fma_f32 v17, -v17, v20, v19
	v_div_fmas_f32 v17, v17, v18, v20
	v_div_fixup_f32 v15, v17, v15, v16
	v_div_scale_f32 v16, s[0:1], v14, v14, v9
	v_rcp_f32_e32 v17, v16
	s_nop 0
	v_fma_f32 v18, -v16, v17, 1.0
	v_fmac_f32_e32 v17, v18, v17
	v_div_scale_f32 v18, vcc, v9, v14, v9
	v_mul_f32_e32 v19, v18, v17
	v_fma_f32 v20, -v16, v19, v18
	v_fmac_f32_e32 v19, v20, v17
	v_fma_f32 v16, -v16, v19, v18
	v_div_fmas_f32 v16, v16, v17, v19
	v_div_fixup_f32 v14, v16, v14, v9
	v_lshlrev_b32_e32 v9, 16, v5
	v_and_b32_e32 v5, 0xffff0000, v5
	v_mul_f32_e32 v16, 0xbfb8aa3b, v9
	v_mul_f32_e32 v17, 0xbfb8aa3b, v5
	v_exp_f32_e32 v16, v16
	v_exp_f32_e32 v17, v17
	v_pk_mul_f32 v[14:15], v[12:13], v[14:15]
	v_pk_mul_f32 v[12:13], v[108:109], v[6:7] op_sel_hi:[1,0]
	v_pk_add_f32 v[16:17], v[16:17], 1.0 op_sel_hi:[1,0]
	s_nop 0
	v_div_scale_f32 v18, s[0:1], v17, v17, v5
	v_rcp_f32_e32 v19, v18
	v_pk_fma_f32 v[12:13], v[4:5], v[92:93], v[12:13] op_sel_hi:[0,1,1]
	v_pk_fma_f32 v[12:13], v[124:125], v[8:9], v[12:13] op_sel_hi:[1,0,1]
	v_fma_f32 v20, -v18, v19, 1.0
	v_fmac_f32_e32 v19, v20, v19
	v_div_scale_f32 v20, vcc, v5, v17, v5
	v_mul_f32_e32 v21, v20, v19
	v_fma_f32 v22, -v18, v21, v20
	v_fmac_f32_e32 v21, v22, v19
	v_fma_f32 v18, -v18, v21, v20
	v_div_fmas_f32 v18, v18, v19, v21
	v_div_fixup_f32 v17, v18, v17, v5
	v_div_scale_f32 v5, s[0:1], v16, v16, v9
	v_rcp_f32_e32 v18, v5
	s_nop 0
	v_fma_f32 v19, -v5, v18, 1.0
	v_fmac_f32_e32 v18, v19, v18
	v_div_scale_f32 v19, vcc, v9, v16, v9
	v_mul_f32_e32 v20, v19, v18
	v_fma_f32 v21, -v5, v20, v19
	v_fmac_f32_e32 v20, v21, v18
	v_fma_f32 v5, -v5, v20, v19
	v_div_fmas_f32 v5, v5, v18, v20
	v_div_fixup_f32 v16, v5, v16, v9
	v_lshlrev_b32_e32 v5, 16, v7
	v_and_b32_e32 v7, 0xffff0000, v7
	v_pk_mul_f32 v[16:17], v[12:13], v[16:17]
	v_pk_mul_f32 v[12:13], v[110:111], v[6:7] op_sel_hi:[1,0]
	s_nop 0
	v_pk_fma_f32 v[12:13], v[4:5], v[94:95], v[12:13] op_sel_hi:[0,1,1]
	v_pk_fma_f32 v[12:13], v[126:127], v[8:9], v[12:13] op_sel_hi:[1,0,1]
	v_mul_f32_e32 v9, 0xbfb8aa3b, v5
	v_exp_f32_e32 v18, v9
	v_mul_f32_e32 v9, 0xbfb8aa3b, v7
	v_exp_f32_e32 v19, v9
	s_nop 0
	v_pk_add_f32 v[18:19], v[18:19], 1.0 op_sel_hi:[1,0]
	s_nop 0
	v_div_scale_f32 v9, s[0:1], v19, v19, v7
	v_rcp_f32_e32 v20, v9
	s_nop 0
	v_fma_f32 v21, -v9, v20, 1.0
	v_fmac_f32_e32 v20, v21, v20
	v_div_scale_f32 v21, vcc, v7, v19, v7
	v_mul_f32_e32 v22, v21, v20
	v_fma_f32 v23, -v9, v22, v21
	v_fmac_f32_e32 v22, v23, v20
	v_fma_f32 v9, -v9, v22, v21
	v_div_fmas_f32 v9, v9, v20, v22
	v_div_fixup_f32 v19, v9, v19, v7
	v_div_scale_f32 v7, s[0:1], v18, v18, v5
	v_rcp_f32_e32 v9, v7
	s_nop 0
	v_fma_f32 v20, -v7, v9, 1.0
	v_fmac_f32_e32 v9, v20, v9
	v_div_scale_f32 v20, vcc, v5, v18, v5
	v_mul_f32_e32 v21, v20, v9
	v_fma_f32 v22, -v7, v21, v20
	v_fmac_f32_e32 v21, v22, v9
	v_fma_f32 v7, -v7, v21, v20
	v_div_fmas_f32 v7, v7, v9, v21
	v_div_fixup_f32 v18, v7, v18, v5
	v_pk_mul_f32 v[18:19], v[12:13], v[18:19]
	v_cvt_pk_bf16_f32 v12, v2, v3
	v_cvt_pk_bf16_f32 v13, v14, v15
	v_cvt_pk_bf16_f32 v14, v16, v17
	v_cvt_pk_bf16_f32 v15, v18, v19
	s_nop 0
	v_permlane32_swap_b32_e32 v12, v14
	v_permlane32_swap_b32_e32 v13, v15
	global_store_dwordx4 v[10:11], v[12:15], off offset:32
	s_waitcnt vmcnt(3)
	v_mov_b32_e32 v5, v134
	s_nop 1
	v_mov_b32_e32 v12, v132
	s_nop 1
	v_permlane32_swap_b32_e32 v12, v5
	v_lshlrev_b32_e32 v9, 16, v12
	v_and_b32_e32 v12, 0xffff0000, v12
	v_mov_b32_e32 v7, v135
	v_mul_f32_e32 v14, 0xbfb8aa3b, v9
	v_mul_f32_e32 v15, 0xbfb8aa3b, v12
	v_exp_f32_e32 v14, v14
	v_exp_f32_e32 v15, v15
	v_mov_b32_e32 v13, v133
	s_nop 1
	v_permlane32_swap_b32_e32 v13, v7
	v_pk_mul_f32 v[2:3], v[48:49], v[6:7] op_sel_hi:[1,0]
	v_pk_add_f32 v[14:15], v[14:15], 1.0 op_sel_hi:[1,0]
	v_pk_fma_f32 v[2:3], v[4:5], v[32:33], v[2:3] op_sel_hi:[0,1,1]
	v_div_scale_f32 v16, s[0:1], v15, v15, v12
	v_rcp_f32_e32 v17, v16
	v_pk_fma_f32 v[2:3], v[64:65], v[8:9], v[2:3] op_sel_hi:[1,0,1]
	v_fma_f32 v18, -v16, v17, 1.0
	v_fmac_f32_e32 v17, v18, v17
	v_div_scale_f32 v18, vcc, v12, v15, v12
	v_mul_f32_e32 v19, v18, v17
	v_fma_f32 v20, -v16, v19, v18
	v_fmac_f32_e32 v19, v20, v17
	v_fma_f32 v16, -v16, v19, v18
	v_div_fmas_f32 v16, v16, v17, v19
	v_div_fixup_f32 v15, v16, v15, v12
	v_div_scale_f32 v12, s[0:1], v14, v14, v9
	v_rcp_f32_e32 v16, v12
	s_nop 0
	v_fma_f32 v17, -v12, v16, 1.0
	v_fmac_f32_e32 v16, v17, v16
	v_div_scale_f32 v17, vcc, v9, v14, v9
	v_mul_f32_e32 v18, v17, v16
	v_fma_f32 v19, -v12, v18, v17
	v_fmac_f32_e32 v18, v19, v16
	v_fma_f32 v12, -v12, v18, v17
	v_div_fmas_f32 v12, v12, v16, v18
	v_div_fixup_f32 v14, v12, v14, v9
	v_lshlrev_b32_e32 v9, 16, v13
	v_and_b32_e32 v16, 0xffff0000, v13
	v_pk_mul_f32 v[2:3], v[2:3], v[14:15]
	v_mul_f32_e32 v14, 0xbfb8aa3b, v9
	v_mul_f32_e32 v15, 0xbfb8aa3b, v16
	v_exp_f32_e32 v14, v14
	v_exp_f32_e32 v15, v15
	v_pk_mul_f32 v[12:13], v[50:51], v[6:7] op_sel_hi:[1,0]
	v_pk_add_f32 v[14:15], v[14:15], 1.0 op_sel_hi:[1,0]
	s_nop 0
	v_div_scale_f32 v17, s[0:1], v15, v15, v16
	v_rcp_f32_e32 v18, v17
	v_pk_fma_f32 v[12:13], v[4:5], v[34:35], v[12:13] op_sel_hi:[0,1,1]
	v_pk_fma_f32 v[12:13], v[66:67], v[8:9], v[12:13] op_sel_hi:[1,0,1]
	v_fma_f32 v19, -v17, v18, 1.0
	v_fmac_f32_e32 v18, v19, v18
	v_div_scale_f32 v19, vcc, v16, v15, v16
	v_mul_f32_e32 v20, v19, v18
	v_fma_f32 v21, -v17, v20, v19
	v_fmac_f32_e32 v20, v21, v18
	v_fma_f32 v17, -v17, v20, v19
	v_div_fmas_f32 v17, v17, v18, v20
	v_div_fixup_f32 v15, v17, v15, v16
	v_div_scale_f32 v16, s[0:1], v14, v14, v9
	v_rcp_f32_e32 v17, v16
	s_nop 0
	v_fma_f32 v18, -v16, v17, 1.0
	v_fmac_f32_e32 v17, v18, v17
	v_div_scale_f32 v18, vcc, v9, v14, v9
	v_mul_f32_e32 v19, v18, v17
	v_fma_f32 v20, -v16, v19, v18
	v_fmac_f32_e32 v19, v20, v17
	v_fma_f32 v16, -v16, v19, v18
	v_div_fmas_f32 v16, v16, v17, v19
	v_div_fixup_f32 v14, v16, v14, v9
	v_lshlrev_b32_e32 v9, 16, v5
	v_and_b32_e32 v5, 0xffff0000, v5
	v_mul_f32_e32 v16, 0xbfb8aa3b, v9
	v_mul_f32_e32 v17, 0xbfb8aa3b, v5
	v_exp_f32_e32 v16, v16
	v_exp_f32_e32 v17, v17
	v_pk_mul_f32 v[14:15], v[12:13], v[14:15]
	v_pk_mul_f32 v[12:13], v[52:53], v[6:7] op_sel_hi:[1,0]
	v_pk_add_f32 v[16:17], v[16:17], 1.0 op_sel_hi:[1,0]
	s_nop 0
	v_div_scale_f32 v18, s[0:1], v17, v17, v5
	v_rcp_f32_e32 v19, v18
	v_pk_fma_f32 v[12:13], v[4:5], v[36:37], v[12:13] op_sel_hi:[0,1,1]
	v_pk_fma_f32 v[12:13], v[68:69], v[8:9], v[12:13] op_sel_hi:[1,0,1]
	v_fma_f32 v20, -v18, v19, 1.0
	v_fmac_f32_e32 v19, v20, v19
	v_div_scale_f32 v20, vcc, v5, v17, v5
	v_mul_f32_e32 v21, v20, v19
	v_fma_f32 v22, -v18, v21, v20
	v_fmac_f32_e32 v21, v22, v19
	v_fma_f32 v18, -v18, v21, v20
	v_div_fmas_f32 v18, v18, v19, v21
	v_div_fixup_f32 v17, v18, v17, v5
	v_div_scale_f32 v5, s[0:1], v16, v16, v9
	v_rcp_f32_e32 v18, v5
	s_nop 0
	v_fma_f32 v19, -v5, v18, 1.0
	v_fmac_f32_e32 v18, v19, v18
	v_div_scale_f32 v19, vcc, v9, v16, v9
	v_mul_f32_e32 v20, v19, v18
	v_fma_f32 v21, -v5, v20, v19
	v_fmac_f32_e32 v20, v21, v18
	v_fma_f32 v5, -v5, v20, v19
	v_div_fmas_f32 v5, v5, v18, v20
	v_div_fixup_f32 v16, v5, v16, v9
	v_lshlrev_b32_e32 v5, 16, v7
	v_and_b32_e32 v7, 0xffff0000, v7
	v_pk_mul_f32 v[16:17], v[12:13], v[16:17]
	v_pk_mul_f32 v[12:13], v[54:55], v[6:7] op_sel_hi:[1,0]
	s_nop 0
	v_pk_fma_f32 v[12:13], v[4:5], v[38:39], v[12:13] op_sel_hi:[0,1,1]
	v_pk_fma_f32 v[12:13], v[70:71], v[8:9], v[12:13] op_sel_hi:[1,0,1]
	v_mul_f32_e32 v9, 0xbfb8aa3b, v5
	v_exp_f32_e32 v18, v9
	v_mul_f32_e32 v9, 0xbfb8aa3b, v7
	v_exp_f32_e32 v19, v9
	s_nop 0
	v_pk_add_f32 v[18:19], v[18:19], 1.0 op_sel_hi:[1,0]
	s_nop 0
	v_div_scale_f32 v9, s[0:1], v19, v19, v7
	v_rcp_f32_e32 v20, v9
	s_nop 0
	v_fma_f32 v21, -v9, v20, 1.0
	v_fmac_f32_e32 v20, v21, v20
	v_div_scale_f32 v21, vcc, v7, v19, v7
	v_mul_f32_e32 v22, v21, v20
	v_fma_f32 v23, -v9, v22, v21
	v_fmac_f32_e32 v22, v23, v20
	v_fma_f32 v9, -v9, v22, v21
	v_div_fmas_f32 v9, v9, v20, v22
	v_div_fixup_f32 v19, v9, v19, v7
	v_div_scale_f32 v7, s[0:1], v18, v18, v5
	v_rcp_f32_e32 v9, v7
	s_nop 0
	v_fma_f32 v20, -v7, v9, 1.0
	v_fmac_f32_e32 v9, v20, v9
	v_div_scale_f32 v20, vcc, v5, v18, v5
	v_mul_f32_e32 v21, v20, v9
	v_fma_f32 v22, -v7, v21, v20
	v_fmac_f32_e32 v21, v22, v9
	v_fma_f32 v7, -v7, v21, v20
	v_div_fmas_f32 v7, v7, v9, v21
	v_div_fixup_f32 v18, v7, v18, v5
	v_pk_mul_f32 v[18:19], v[12:13], v[18:19]
	v_cvt_pk_bf16_f32 v12, v2, v3
	v_cvt_pk_bf16_f32 v13, v14, v15
	v_cvt_pk_bf16_f32 v14, v16, v17
	v_cvt_pk_bf16_f32 v15, v18, v19
	s_nop 0
	v_permlane32_swap_b32_e32 v12, v14
	v_permlane32_swap_b32_e32 v13, v15
	global_store_dwordx4 v[10:11], v[12:15], off offset:64
	s_waitcnt vmcnt(3)
	v_mov_b32_e32 v5, v138
	s_nop 1
	v_mov_b32_e32 v0, v136
	s_nop 1
	v_permlane32_swap_b32_e32 v0, v5
	v_lshlrev_b32_e32 v9, 16, v0
	v_and_b32_e32 v0, 0xffff0000, v0
	v_mul_f32_e32 v12, 0xbfb8aa3b, v9
	v_mul_f32_e32 v13, 0xbfb8aa3b, v0
	v_exp_f32_e32 v12, v12
	v_exp_f32_e32 v13, v13
	v_mov_b32_e32 v7, v139
	s_nop 1
	v_mov_b32_e32 v1, v137
	s_nop 1
	v_permlane32_swap_b32_e32 v1, v7
	v_pk_add_f32 v[12:13], v[12:13], 1.0 op_sel_hi:[1,0]
	v_pk_mul_f32 v[2:3], v[56:57], v[6:7] op_sel_hi:[1,0]
	v_div_scale_f32 v14, s[0:1], v13, v13, v0
	v_rcp_f32_e32 v15, v14
	v_pk_fma_f32 v[2:3], v[4:5], v[40:41], v[2:3] op_sel_hi:[0,1,1]
	v_pk_fma_f32 v[2:3], v[72:73], v[8:9], v[2:3] op_sel_hi:[1,0,1]
	v_fma_f32 v16, -v14, v15, 1.0
	v_fmac_f32_e32 v15, v16, v15
	v_div_scale_f32 v16, vcc, v0, v13, v0
	v_mul_f32_e32 v17, v16, v15
	v_fma_f32 v18, -v14, v17, v16
	v_fmac_f32_e32 v17, v18, v15
	v_fma_f32 v14, -v14, v17, v16
	v_div_fmas_f32 v14, v14, v15, v17
	v_div_fixup_f32 v13, v14, v13, v0
	v_div_scale_f32 v0, s[0:1], v12, v12, v9
	v_rcp_f32_e32 v14, v0
	s_nop 0
	v_fma_f32 v15, -v0, v14, 1.0
	v_fmac_f32_e32 v14, v15, v14
	v_div_scale_f32 v15, vcc, v9, v12, v9
	v_mul_f32_e32 v16, v15, v14
	v_fma_f32 v17, -v0, v16, v15
	v_fmac_f32_e32 v16, v17, v14
	v_fma_f32 v0, -v0, v16, v15
	v_div_fmas_f32 v0, v0, v14, v16
	v_div_fixup_f32 v12, v0, v12, v9
	v_lshlrev_b32_e32 v9, 16, v1
	v_and_b32_e32 v14, 0xffff0000, v1
	v_pk_mul_f32 v[2:3], v[2:3], v[12:13]
	v_mul_f32_e32 v12, 0xbfb8aa3b, v9
	v_mul_f32_e32 v13, 0xbfb8aa3b, v14
	v_exp_f32_e32 v12, v12
	v_exp_f32_e32 v13, v13
	v_pk_mul_f32 v[0:1], v[58:59], v[6:7] op_sel_hi:[1,0]
	v_cvt_pk_bf16_f32 v2, v2, v3
	v_pk_fma_f32 v[0:1], v[4:5], v[42:43], v[0:1] op_sel_hi:[0,1,1]
	v_pk_add_f32 v[12:13], v[12:13], 1.0 op_sel_hi:[1,0]
	v_pk_fma_f32 v[0:1], v[74:75], v[8:9], v[0:1] op_sel_hi:[1,0,1]
	v_div_scale_f32 v15, s[0:1], v13, v13, v14
	v_rcp_f32_e32 v16, v15
	s_nop 0
	v_fma_f32 v17, -v15, v16, 1.0
	v_fmac_f32_e32 v16, v17, v16
	v_div_scale_f32 v17, vcc, v14, v13, v14
	v_mul_f32_e32 v18, v17, v16
	v_fma_f32 v19, -v15, v18, v17
	v_fmac_f32_e32 v18, v19, v16
	v_fma_f32 v15, -v15, v18, v17
	v_div_fmas_f32 v15, v15, v16, v18
	v_div_fixup_f32 v13, v15, v13, v14
	v_div_scale_f32 v14, s[0:1], v12, v12, v9
	v_rcp_f32_e32 v15, v14
	s_nop 0
	v_fma_f32 v16, -v14, v15, 1.0
	v_fmac_f32_e32 v15, v16, v15
	v_div_scale_f32 v16, vcc, v9, v12, v9
	v_mul_f32_e32 v17, v16, v15
	v_fma_f32 v18, -v14, v17, v16
	v_fmac_f32_e32 v17, v18, v15
	v_fma_f32 v14, -v14, v17, v16
	v_div_fmas_f32 v14, v14, v15, v17
	v_div_fixup_f32 v12, v14, v12, v9
	v_lshlrev_b32_e32 v9, 16, v5
	v_and_b32_e32 v5, 0xffff0000, v5
	v_mul_f32_e32 v14, 0xbfb8aa3b, v9
	v_mul_f32_e32 v15, 0xbfb8aa3b, v5
	v_exp_f32_e32 v14, v14
	v_exp_f32_e32 v15, v15
	v_pk_mul_f32 v[0:1], v[0:1], v[12:13]
	v_pk_mul_f32 v[12:13], v[60:61], v[6:7] op_sel_hi:[1,0]
	v_cvt_pk_bf16_f32 v3, v0, v1
	v_pk_add_f32 v[14:15], v[14:15], 1.0 op_sel_hi:[1,0]
	v_pk_fma_f32 v[12:13], v[4:5], v[44:45], v[12:13] op_sel_hi:[0,1,1]
	v_div_scale_f32 v16, s[0:1], v15, v15, v5
	v_rcp_f32_e32 v17, v16
	v_pk_fma_f32 v[12:13], v[76:77], v[8:9], v[12:13] op_sel_hi:[1,0,1]
	v_fma_f32 v18, -v16, v17, 1.0
	v_fmac_f32_e32 v17, v18, v17
	v_div_scale_f32 v18, vcc, v5, v15, v5
	v_mul_f32_e32 v19, v18, v17
	v_fma_f32 v20, -v16, v19, v18
	v_fmac_f32_e32 v19, v20, v17
	v_fma_f32 v16, -v16, v19, v18
	v_div_fmas_f32 v16, v16, v17, v19
	v_div_fixup_f32 v15, v16, v15, v5
	v_div_scale_f32 v5, s[0:1], v14, v14, v9
	v_rcp_f32_e32 v16, v5
	s_nop 0
	v_fma_f32 v17, -v5, v16, 1.0
	v_fmac_f32_e32 v16, v17, v16
	v_div_scale_f32 v17, vcc, v9, v14, v9
	v_mul_f32_e32 v18, v17, v16
	v_fma_f32 v19, -v5, v18, v17
	v_fmac_f32_e32 v18, v19, v16
	v_fma_f32 v5, -v5, v18, v17
	v_div_fmas_f32 v5, v5, v16, v18
	v_div_fixup_f32 v14, v5, v14, v9
	v_pk_mul_f32 v[12:13], v[12:13], v[14:15]
	v_lshlrev_b32_e32 v9, 16, v7
	v_and_b32_e32 v14, 0xffff0000, v7
	v_pk_mul_f32 v[6:7], v[62:63], v[6:7] op_sel_hi:[1,0]
	s_nop 0
	v_pk_fma_f32 v[4:5], v[4:5], v[46:47], v[6:7] op_sel_hi:[0,1,1]
	v_mul_f32_e32 v6, 0xbfb8aa3b, v9
	v_mul_f32_e32 v7, 0xbfb8aa3b, v14
	v_exp_f32_e32 v6, v6
	v_exp_f32_e32 v7, v7
	v_pk_fma_f32 v[4:5], v[78:79], v[8:9], v[4:5] op_sel_hi:[1,0,1]
	v_pk_add_f32 v[6:7], v[6:7], 1.0 op_sel_hi:[1,0]
	s_nop 0
	v_div_scale_f32 v8, s[0:1], v7, v7, v14
	v_rcp_f32_e32 v15, v8
	s_nop 0
	v_fma_f32 v16, -v8, v15, 1.0
	v_fmac_f32_e32 v15, v16, v15
	v_div_scale_f32 v16, vcc, v14, v7, v14
	v_mul_f32_e32 v17, v16, v15
	v_fma_f32 v18, -v8, v17, v16
	v_fmac_f32_e32 v17, v18, v15
	v_fma_f32 v8, -v8, v17, v16
	v_div_fmas_f32 v8, v8, v15, v17
	v_div_fixup_f32 v7, v8, v7, v14
	v_div_scale_f32 v8, s[0:1], v6, v6, v9
	v_rcp_f32_e32 v14, v8
	s_nop 0
	v_fma_f32 v15, -v8, v14, 1.0
	v_fmac_f32_e32 v14, v15, v14
	v_div_scale_f32 v15, vcc, v9, v6, v9
	v_mul_f32_e32 v16, v15, v14
	v_fma_f32 v17, -v8, v16, v15
	v_fmac_f32_e32 v16, v17, v14
	v_fma_f32 v8, -v8, v16, v15
	v_div_fmas_f32 v8, v8, v14, v16
	v_div_fixup_f32 v6, v8, v6, v9
	v_pk_mul_f32 v[6:7], v[4:5], v[6:7]
	v_cvt_pk_bf16_f32 v4, v12, v13
	v_cvt_pk_bf16_f32 v5, v6, v7
	s_nop 0
	v_permlane32_swap_b32_e32 v2, v4
	v_permlane32_swap_b32_e32 v3, v5
	global_store_dwordx4 v[10:11], v[2:5], off offset:96

.LBB0_513:
	s_mov_b64 s[8:9], 0x3e38aa3b
	s_lshl_b32 s0, s1, 1
	s_mov_b32 s1, s9
	v_readlane_b32 s8, v254, 43
	v_lshlrev_b64 v[2:3], 11, v[130:131]
	v_readlane_b32 s9, v254, 44
	v_lshl_add_u64 v[0:1], v[132:133], 0, s[0:1]
	v_mov_b32_e32 v129, v193
	v_lshl_add_u64 v[2:3], s[8:9], 0, v[2:3]
	v_lshl_add_u64 v[2:3], v[2:3], 0, s[0:1]
	v_lshl_add_u64 v[6:7], v[0:1], 0, v[128:129]
	s_mov_b64 s[0:1], 0x1a00
	v_lshl_add_u64 v[0:1], v[6:7], 0, s[0:1]
	v_add_co_u32_e32 v6, vcc, 0x1000, v6
	v_lshl_add_u64 v[2:3], v[2:3], 0, v[128:129]
	s_nop 0
	v_addc_co_u32_e32 v7, vcc, 0, v7, vcc
	global_load_dwordx4 v[6:9], v[6:7], off offset:2560
	global_load_dwordx4 v[64:67], v[0:1], off offset:32
	global_load_dwordx4 v[68:71], v[0:1], off offset:64
	global_load_dwordx4 v[72:75], v[0:1], off offset:96
	s_mov_b64 s[0:1], 0xd210600
	v_lshl_add_u64 v[4:5], v[2:3], 0, s[0:1]
	v_readlane_b32 s76, v254, 37
	v_readlane_b32 s77, v254, 38
	s_mov_b64 s[8:9], 0
	s_waitcnt vmcnt(3) lgkmcnt(0)
	v_mov_b32_e32 v12, v8
	s_nop 1
	v_permlane32_swap_b32_e32 v6, v12
	v_lshlrev_b32_e32 v10, 16, v6
	v_and_b32_e32 v6, 0xffff0000, v6
	v_mov_b32_e32 v14, v9
	v_mul_f32_e32 v8, 0xbfb8aa3b, v10
	v_mul_f32_e32 v9, 0xbfb8aa3b, v6
	v_exp_f32_e32 v8, v8
	v_exp_f32_e32 v9, v9
	v_permlane32_swap_b32_e32 v7, v14
	v_pk_add_f32 v[8:9], v[8:9], 1.0 op_sel_hi:[1,0]
	s_nop 0
	v_div_scale_f32 v11, s[0:1], v9, v9, v6
	v_rcp_f32_e32 v13, v11
	s_nop 0
	v_fma_f32 v15, -v11, v13, 1.0
	v_fmac_f32_e32 v13, v15, v13
	v_div_scale_f32 v15, vcc, v6, v9, v6
	v_mul_f32_e32 v16, v15, v13
	v_fma_f32 v17, -v11, v16, v15
	v_fmac_f32_e32 v16, v17, v13
	v_fma_f32 v11, -v11, v16, v15
	v_div_fmas_f32 v11, v11, v13, v16
	v_div_fixup_f32 v9, v11, v9, v6
	v_div_scale_f32 v6, s[0:1], v8, v8, v10
	v_rcp_f32_e32 v11, v6
	s_nop 0
	v_fma_f32 v13, -v6, v11, 1.0
	v_fmac_f32_e32 v11, v13, v11
	v_div_scale_f32 v13, vcc, v10, v8, v10
	v_mul_f32_e32 v15, v13, v11
	v_fma_f32 v16, -v6, v15, v13
	v_fmac_f32_e32 v15, v16, v11
	v_fma_f32 v6, -v6, v15, v13
	v_div_fmas_f32 v6, v6, v11, v15
	v_div_fixup_f32 v8, v6, v8, v10
	v_lshlrev_b32_e32 v10, 16, v7
	v_and_b32_e32 v11, 0xffff0000, v7
	v_mul_f32_e32 v6, 0xbfb8aa3b, v10
	v_mul_f32_e32 v7, 0xbfb8aa3b, v11
	v_exp_f32_e32 v6, v6
	v_exp_f32_e32 v7, v7
	v_pk_mul_f32 v[8:9], v[48:49], v[8:9]
	v_pk_add_f32 v[6:7], v[6:7], 1.0 op_sel_hi:[1,0]
	s_nop 0
	v_div_scale_f32 v13, s[0:1], v7, v7, v11
	v_rcp_f32_e32 v15, v13
	s_nop 0
	v_fma_f32 v16, -v13, v15, 1.0
	v_fmac_f32_e32 v15, v16, v15
	v_div_scale_f32 v16, vcc, v11, v7, v11
	v_mul_f32_e32 v17, v16, v15
	v_fma_f32 v18, -v13, v17, v16
	v_fmac_f32_e32 v17, v18, v15
	v_fma_f32 v13, -v13, v17, v16
	v_div_fmas_f32 v13, v13, v15, v17
	v_div_fixup_f32 v7, v13, v7, v11
	v_div_scale_f32 v11, s[0:1], v6, v6, v10
	v_rcp_f32_e32 v13, v11
	s_nop 0
	v_fma_f32 v15, -v11, v13, 1.0
	v_fmac_f32_e32 v13, v15, v13
	v_div_scale_f32 v15, vcc, v10, v6, v10
	v_mul_f32_e32 v16, v15, v13
	v_fma_f32 v17, -v11, v16, v15
	v_fmac_f32_e32 v16, v17, v13
	v_fma_f32 v11, -v11, v16, v15
	v_div_fmas_f32 v11, v11, v13, v16
	v_div_fixup_f32 v6, v11, v6, v10
	v_lshlrev_b32_e32 v13, 16, v12
	v_and_b32_e32 v12, 0xffff0000, v12
	v_pk_mul_f32 v[10:11], v[50:51], v[6:7]
	v_mul_f32_e32 v6, 0xbfb8aa3b, v13
	v_mul_f32_e32 v7, 0xbfb8aa3b, v12
	v_exp_f32_e32 v6, v6
	v_exp_f32_e32 v7, v7
	s_nop 0
	v_pk_add_f32 v[6:7], v[6:7], 1.0 op_sel_hi:[1,0]
	s_nop 0
	v_div_scale_f32 v15, s[0:1], v7, v7, v12
	v_rcp_f32_e32 v16, v15
	s_nop 0
	v_fma_f32 v17, -v15, v16, 1.0
	v_fmac_f32_e32 v16, v17, v16
	v_div_scale_f32 v17, vcc, v12, v7, v12
	v_mul_f32_e32 v18, v17, v16
	v_fma_f32 v19, -v15, v18, v17
	v_fmac_f32_e32 v18, v19, v16
	v_fma_f32 v15, -v15, v18, v17
	v_div_fmas_f32 v15, v15, v16, v18
	v_div_fixup_f32 v7, v15, v7, v12
	v_div_scale_f32 v12, s[0:1], v6, v6, v13
	v_rcp_f32_e32 v15, v12
	s_nop 0
	v_fma_f32 v16, -v12, v15, 1.0
	v_fmac_f32_e32 v15, v16, v15
	v_div_scale_f32 v16, vcc, v13, v6, v13
	v_mul_f32_e32 v17, v16, v15
	v_fma_f32 v18, -v12, v17, v16
	v_fmac_f32_e32 v17, v18, v15
	v_fma_f32 v12, -v12, v17, v16
	v_div_fmas_f32 v12, v12, v15, v17
	v_div_fixup_f32 v6, v12, v6, v13
	v_lshlrev_b32_e32 v15, 16, v14
	v_and_b32_e32 v14, 0xffff0000, v14
	v_pk_mul_f32 v[12:13], v[52:53], v[6:7]
	v_mul_f32_e32 v6, 0xbfb8aa3b, v15
	v_mul_f32_e32 v7, 0xbfb8aa3b, v14
	v_exp_f32_e32 v6, v6
	v_exp_f32_e32 v7, v7
	s_nop 0
	v_pk_add_f32 v[6:7], v[6:7], 1.0 op_sel_hi:[1,0]
	s_nop 0
	v_div_scale_f32 v16, s[0:1], v7, v7, v14
	v_rcp_f32_e32 v17, v16
	s_nop 0
	v_fma_f32 v18, -v16, v17, 1.0
	v_fmac_f32_e32 v17, v18, v17
	v_div_scale_f32 v18, vcc, v14, v7, v14
	v_mul_f32_e32 v19, v18, v17
	v_fma_f32 v20, -v16, v19, v18
	v_fmac_f32_e32 v19, v20, v17
	v_fma_f32 v16, -v16, v19, v18
	v_div_fmas_f32 v16, v16, v17, v19
	v_div_fixup_f32 v7, v16, v7, v14
	v_div_scale_f32 v14, s[0:1], v6, v6, v15
	v_rcp_f32_e32 v16, v14
	s_mov_b32 s0, 0xd210000
	v_fma_f32 v17, -v14, v16, 1.0
	v_fmac_f32_e32 v16, v17, v16
	v_div_scale_f32 v17, vcc, v15, v6, v15
	v_mul_f32_e32 v18, v17, v16
	v_fma_f32 v19, -v14, v18, v17
	v_fmac_f32_e32 v18, v19, v16
	v_fma_f32 v14, -v14, v18, v17
	v_div_fmas_f32 v14, v14, v16, v18
	v_div_fixup_f32 v6, v14, v6, v15
	v_pk_mul_f32 v[14:15], v[54:55], v[6:7]
	v_cvt_pk_bf16_f32 v6, v8, v9
	v_cvt_pk_bf16_f32 v7, v10, v11
	v_cvt_pk_bf16_f32 v8, v12, v13
	v_cvt_pk_bf16_f32 v9, v14, v15
	v_add_co_u32_e32 v2, vcc, s0, v2
	v_permlane32_swap_b32_e32 v6, v8
	v_permlane32_swap_b32_e32 v7, v9
	v_addc_co_u32_e32 v3, vcc, 0, v3, vcc
	global_store_dwordx4 v[2:3], v[6:9], off offset:1536
	s_waitcnt vmcnt(3)
	v_mov_b32_e32 v10, v66
	s_nop 1
	v_mov_b32_e32 v6, v64
	s_nop 1
	v_permlane32_swap_b32_e32 v6, v10
	v_lshlrev_b32_e32 v8, 16, v6
	v_and_b32_e32 v6, 0xffff0000, v6
	v_mul_f32_e32 v2, 0xbfb8aa3b, v8
	v_mul_f32_e32 v3, 0xbfb8aa3b, v6
	v_exp_f32_e32 v2, v2
	v_exp_f32_e32 v3, v3
	v_mov_b32_e32 v12, v67
	s_nop 1
	v_mov_b32_e32 v7, v65
	s_nop 1
	v_permlane32_swap_b32_e32 v7, v12
	v_pk_add_f32 v[2:3], v[2:3], 1.0 op_sel_hi:[1,0]
	s_nop 0
	v_div_scale_f32 v9, s[0:1], v3, v3, v6
	v_rcp_f32_e32 v11, v9
	s_nop 0
	v_fma_f32 v13, -v9, v11, 1.0
	v_fmac_f32_e32 v11, v13, v11
	v_div_scale_f32 v13, vcc, v6, v3, v6
	v_mul_f32_e32 v14, v13, v11
	v_fma_f32 v15, -v9, v14, v13
	v_fmac_f32_e32 v14, v15, v11
	v_fma_f32 v9, -v9, v14, v13
	v_div_fmas_f32 v9, v9, v11, v14
	v_div_fixup_f32 v3, v9, v3, v6
	v_div_scale_f32 v6, s[0:1], v2, v2, v8
	v_rcp_f32_e32 v9, v6
	s_nop 0
	v_fma_f32 v11, -v6, v9, 1.0
	v_fmac_f32_e32 v9, v11, v9
	v_div_scale_f32 v11, vcc, v8, v2, v8
	v_mul_f32_e32 v13, v11, v9
	v_fma_f32 v14, -v6, v13, v11
	v_fmac_f32_e32 v13, v14, v9
	v_fma_f32 v6, -v6, v13, v11
	v_div_fmas_f32 v6, v6, v9, v13
	v_div_fixup_f32 v2, v6, v2, v8
	v_lshlrev_b32_e32 v8, 16, v7
	v_and_b32_e32 v9, 0xffff0000, v7
	v_mul_f32_e32 v6, 0xbfb8aa3b, v8
	v_mul_f32_e32 v7, 0xbfb8aa3b, v9
	v_exp_f32_e32 v6, v6
	v_exp_f32_e32 v7, v7
	v_pk_mul_f32 v[2:3], v[56:57], v[2:3]
	v_pk_add_f32 v[6:7], v[6:7], 1.0 op_sel_hi:[1,0]
	s_nop 0
	v_div_scale_f32 v11, s[0:1], v7, v7, v9
	v_rcp_f32_e32 v13, v11
	s_nop 0
	v_fma_f32 v14, -v11, v13, 1.0
	v_fmac_f32_e32 v13, v14, v13
	v_div_scale_f32 v14, vcc, v9, v7, v9
	v_mul_f32_e32 v15, v14, v13
	v_fma_f32 v16, -v11, v15, v14
	v_fmac_f32_e32 v15, v16, v13
	v_fma_f32 v11, -v11, v15, v14
	v_div_fmas_f32 v11, v11, v13, v15
	v_div_fixup_f32 v7, v11, v7, v9
	v_div_scale_f32 v9, s[0:1], v6, v6, v8
	v_rcp_f32_e32 v11, v9
	s_nop 0
	v_fma_f32 v13, -v9, v11, 1.0
	v_fmac_f32_e32 v11, v13, v11
	v_div_scale_f32 v13, vcc, v8, v6, v8
	v_mul_f32_e32 v14, v13, v11
	v_fma_f32 v15, -v9, v14, v13
	v_fmac_f32_e32 v14, v15, v11
	v_fma_f32 v9, -v9, v14, v13
	v_div_fmas_f32 v9, v9, v11, v14
	v_div_fixup_f32 v6, v9, v6, v8
	v_lshlrev_b32_e32 v11, 16, v10
	v_and_b32_e32 v10, 0xffff0000, v10
	v_pk_mul_f32 v[8:9], v[58:59], v[6:7]
	v_mul_f32_e32 v6, 0xbfb8aa3b, v11
	v_mul_f32_e32 v7, 0xbfb8aa3b, v10
	v_exp_f32_e32 v6, v6
	v_exp_f32_e32 v7, v7
	s_nop 0
	v_pk_add_f32 v[6:7], v[6:7], 1.0 op_sel_hi:[1,0]
	s_nop 0
	v_div_scale_f32 v13, s[0:1], v7, v7, v10
	v_rcp_f32_e32 v14, v13
	s_nop 0
	v_fma_f32 v15, -v13, v14, 1.0
	v_fmac_f32_e32 v14, v15, v14
	v_div_scale_f32 v15, vcc, v10, v7, v10
	v_mul_f32_e32 v16, v15, v14
	v_fma_f32 v17, -v13, v16, v15
	v_fmac_f32_e32 v16, v17, v14
	v_fma_f32 v13, -v13, v16, v15
	v_div_fmas_f32 v13, v13, v14, v16
	v_div_fixup_f32 v7, v13, v7, v10
	v_div_scale_f32 v10, s[0:1], v6, v6, v11
	v_rcp_f32_e32 v13, v10
	s_nop 0
	v_fma_f32 v14, -v10, v13, 1.0
	v_fmac_f32_e32 v13, v14, v13
	v_div_scale_f32 v14, vcc, v11, v6, v11
	v_mul_f32_e32 v15, v14, v13
	v_fma_f32 v16, -v10, v15, v14
	v_fmac_f32_e32 v15, v16, v13
	v_fma_f32 v10, -v10, v15, v14
	v_div_fmas_f32 v10, v10, v13, v15
	v_div_fixup_f32 v6, v10, v6, v11
	v_lshlrev_b32_e32 v13, 16, v12
	v_and_b32_e32 v12, 0xffff0000, v12
	v_pk_mul_f32 v[10:11], v[60:61], v[6:7]
	v_mul_f32_e32 v6, 0xbfb8aa3b, v13
	v_mul_f32_e32 v7, 0xbfb8aa3b, v12
	v_exp_f32_e32 v6, v6
	v_exp_f32_e32 v7, v7
	s_nop 0
	v_pk_add_f32 v[6:7], v[6:7], 1.0 op_sel_hi:[1,0]
	s_nop 0
	v_div_scale_f32 v14, s[0:1], v7, v7, v12
	v_rcp_f32_e32 v15, v14
	s_nop 0
	v_fma_f32 v16, -v14, v15, 1.0
	v_fmac_f32_e32 v15, v16, v15
	v_div_scale_f32 v16, vcc, v12, v7, v12
	v_mul_f32_e32 v17, v16, v15
	v_fma_f32 v18, -v14, v17, v16
	v_fmac_f32_e32 v17, v18, v15
	v_fma_f32 v14, -v14, v17, v16
	v_div_fmas_f32 v14, v14, v15, v17
	v_div_fixup_f32 v7, v14, v7, v12
	v_div_scale_f32 v12, s[0:1], v6, v6, v13
	v_rcp_f32_e32 v14, v12
	s_nop 0
	v_fma_f32 v15, -v12, v14, 1.0
	v_fmac_f32_e32 v14, v15, v14
	v_div_scale_f32 v15, vcc, v13, v6, v13
	v_mul_f32_e32 v16, v15, v14
	v_fma_f32 v17, -v12, v16, v15
	v_fmac_f32_e32 v16, v17, v14
	v_fma_f32 v12, -v12, v16, v15
	v_div_fmas_f32 v12, v12, v14, v16
	v_div_fixup_f32 v6, v12, v6, v13
	v_pk_mul_f32 v[12:13], v[62:63], v[6:7]
	v_cvt_pk_bf16_f32 v6, v2, v3
	v_cvt_pk_bf16_f32 v7, v8, v9
	v_cvt_pk_bf16_f32 v8, v10, v11
	v_cvt_pk_bf16_f32 v9, v12, v13
	s_nop 0
	v_permlane32_swap_b32_e32 v6, v8
	v_permlane32_swap_b32_e32 v7, v9
	global_store_dwordx4 v[4:5], v[6:9], off offset:32
	s_waitcnt vmcnt(3)
	v_mov_b32_e32 v10, v70
	s_nop 1
	v_mov_b32_e32 v6, v68
	s_nop 1
	v_permlane32_swap_b32_e32 v6, v10
	v_lshlrev_b32_e32 v8, 16, v6
	v_and_b32_e32 v6, 0xffff0000, v6
	v_mul_f32_e32 v2, 0xbfb8aa3b, v8
	v_mul_f32_e32 v3, 0xbfb8aa3b, v6
	v_exp_f32_e32 v2, v2
	v_exp_f32_e32 v3, v3
	v_mov_b32_e32 v12, v71
	s_nop 1
	v_mov_b32_e32 v7, v69
	s_nop 1
	v_permlane32_swap_b32_e32 v7, v12
	v_pk_add_f32 v[2:3], v[2:3], 1.0 op_sel_hi:[1,0]
	s_nop 0
	v_div_scale_f32 v9, s[0:1], v3, v3, v6
	v_rcp_f32_e32 v11, v9
	s_nop 0
	v_fma_f32 v13, -v9, v11, 1.0
	v_fmac_f32_e32 v11, v13, v11
	v_div_scale_f32 v13, vcc, v6, v3, v6
	v_mul_f32_e32 v14, v13, v11
	v_fma_f32 v15, -v9, v14, v13
	v_fmac_f32_e32 v14, v15, v11
	v_fma_f32 v9, -v9, v14, v13
	v_div_fmas_f32 v9, v9, v11, v14
	v_div_fixup_f32 v3, v9, v3, v6
	v_div_scale_f32 v6, s[0:1], v2, v2, v8
	v_rcp_f32_e32 v9, v6
	s_nop 0
	v_fma_f32 v11, -v6, v9, 1.0
	v_fmac_f32_e32 v9, v11, v9
	v_div_scale_f32 v11, vcc, v8, v2, v8
	v_mul_f32_e32 v13, v11, v9
	v_fma_f32 v14, -v6, v13, v11
	v_fmac_f32_e32 v13, v14, v9
	v_fma_f32 v6, -v6, v13, v11
	v_div_fmas_f32 v6, v6, v9, v13
	v_div_fixup_f32 v2, v6, v2, v8
	v_lshlrev_b32_e32 v8, 16, v7
	v_and_b32_e32 v9, 0xffff0000, v7
	v_mul_f32_e32 v6, 0xbfb8aa3b, v8
	v_mul_f32_e32 v7, 0xbfb8aa3b, v9
	v_exp_f32_e32 v6, v6
	v_exp_f32_e32 v7, v7
	v_pk_mul_f32 v[2:3], v[32:33], v[2:3]
	v_pk_add_f32 v[6:7], v[6:7], 1.0 op_sel_hi:[1,0]
	s_nop 0
	v_div_scale_f32 v11, s[0:1], v7, v7, v9
	v_rcp_f32_e32 v13, v11
	s_nop 0
	v_fma_f32 v14, -v11, v13, 1.0
	v_fmac_f32_e32 v13, v14, v13
	v_div_scale_f32 v14, vcc, v9, v7, v9
	v_mul_f32_e32 v15, v14, v13
	v_fma_f32 v16, -v11, v15, v14
	v_fmac_f32_e32 v15, v16, v13
	v_fma_f32 v11, -v11, v15, v14
	v_div_fmas_f32 v11, v11, v13, v15
	v_div_fixup_f32 v7, v11, v7, v9
	v_div_scale_f32 v9, s[0:1], v6, v6, v8
	v_rcp_f32_e32 v11, v9
	s_nop 0
	v_fma_f32 v13, -v9, v11, 1.0
	v_fmac_f32_e32 v11, v13, v11
	v_div_scale_f32 v13, vcc, v8, v6, v8
	v_mul_f32_e32 v14, v13, v11
	v_fma_f32 v15, -v9, v14, v13
	v_fmac_f32_e32 v14, v15, v11
	v_fma_f32 v9, -v9, v14, v13
	v_div_fmas_f32 v9, v9, v11, v14
	v_div_fixup_f32 v6, v9, v6, v8
	v_lshlrev_b32_e32 v11, 16, v10
	v_and_b32_e32 v10, 0xffff0000, v10
	v_pk_mul_f32 v[8:9], v[34:35], v[6:7]
	v_mul_f32_e32 v6, 0xbfb8aa3b, v11
	v_mul_f32_e32 v7, 0xbfb8aa3b, v10
	v_exp_f32_e32 v6, v6
	v_exp_f32_e32 v7, v7
	s_nop 0
	v_pk_add_f32 v[6:7], v[6:7], 1.0 op_sel_hi:[1,0]
	s_nop 0
	v_div_scale_f32 v13, s[0:1], v7, v7, v10
	v_rcp_f32_e32 v14, v13
	s_nop 0
	v_fma_f32 v15, -v13, v14, 1.0
	v_fmac_f32_e32 v14, v15, v14
	v_div_scale_f32 v15, vcc, v10, v7, v10
	v_mul_f32_e32 v16, v15, v14
	v_fma_f32 v17, -v13, v16, v15
	v_fmac_f32_e32 v16, v17, v14
	v_fma_f32 v13, -v13, v16, v15
	v_div_fmas_f32 v13, v13, v14, v16
	v_div_fixup_f32 v7, v13, v7, v10
	v_div_scale_f32 v10, s[0:1], v6, v6, v11
	v_rcp_f32_e32 v13, v10
	s_nop 0
	v_fma_f32 v14, -v10, v13, 1.0
	v_fmac_f32_e32 v13, v14, v13
	v_div_scale_f32 v14, vcc, v11, v6, v11
	v_mul_f32_e32 v15, v14, v13
	v_fma_f32 v16, -v10, v15, v14
	v_fmac_f32_e32 v15, v16, v13
	v_fma_f32 v10, -v10, v15, v14
	v_div_fmas_f32 v10, v10, v13, v15
	v_div_fixup_f32 v6, v10, v6, v11
	v_lshlrev_b32_e32 v13, 16, v12
	v_and_b32_e32 v12, 0xffff0000, v12
	v_pk_mul_f32 v[10:11], v[36:37], v[6:7]
	v_mul_f32_e32 v6, 0xbfb8aa3b, v13
	v_mul_f32_e32 v7, 0xbfb8aa3b, v12
	v_exp_f32_e32 v6, v6
	v_exp_f32_e32 v7, v7
	s_nop 0
	v_pk_add_f32 v[6:7], v[6:7], 1.0 op_sel_hi:[1,0]
	s_nop 0
	v_div_scale_f32 v14, s[0:1], v7, v7, v12
	v_rcp_f32_e32 v15, v14
	s_nop 0
	v_fma_f32 v16, -v14, v15, 1.0
	v_fmac_f32_e32 v15, v16, v15
	v_div_scale_f32 v16, vcc, v12, v7, v12
	v_mul_f32_e32 v17, v16, v15
	v_fma_f32 v18, -v14, v17, v16
	v_fmac_f32_e32 v17, v18, v15
	v_fma_f32 v14, -v14, v17, v16
	v_div_fmas_f32 v14, v14, v15, v17
	v_div_fixup_f32 v7, v14, v7, v12
	v_div_scale_f32 v12, s[0:1], v6, v6, v13
	v_rcp_f32_e32 v14, v12
	s_nop 0
	v_fma_f32 v15, -v12, v14, 1.0
	v_fmac_f32_e32 v14, v15, v14
	v_div_scale_f32 v15, vcc, v13, v6, v13
	v_mul_f32_e32 v16, v15, v14
	v_fma_f32 v17, -v12, v16, v15
	v_fmac_f32_e32 v16, v17, v14
	v_fma_f32 v12, -v12, v16, v15
	v_div_fmas_f32 v12, v12, v14, v16
	v_div_fixup_f32 v6, v12, v6, v13
	v_pk_mul_f32 v[12:13], v[38:39], v[6:7]
	v_cvt_pk_bf16_f32 v6, v2, v3
	v_cvt_pk_bf16_f32 v7, v8, v9
	v_cvt_pk_bf16_f32 v8, v10, v11
	v_cvt_pk_bf16_f32 v9, v12, v13
	s_nop 0
	v_permlane32_swap_b32_e32 v6, v8
	v_permlane32_swap_b32_e32 v7, v9
	global_store_dwordx4 v[4:5], v[6:9], off offset:64
	s_waitcnt vmcnt(3)
	v_mov_b32_e32 v10, v75
	v_mov_b32_e32 v8, v74
	s_nop 1
	v_mov_b32_e32 v0, v72
	s_nop 1
	v_permlane32_swap_b32_e32 v0, v8
	v_lshlrev_b32_e32 v6, 16, v0
	v_and_b32_e32 v0, 0xffff0000, v0
	v_mul_f32_e32 v2, 0xbfb8aa3b, v6
	v_mul_f32_e32 v3, 0xbfb8aa3b, v0
	v_exp_f32_e32 v2, v2
	v_exp_f32_e32 v3, v3
	v_mov_b32_e32 v1, v73
	s_nop 1
	v_permlane32_swap_b32_e32 v1, v10
	v_pk_add_f32 v[2:3], v[2:3], 1.0 op_sel_hi:[1,0]
	s_nop 0
	v_div_scale_f32 v7, s[0:1], v3, v3, v0
	v_rcp_f32_e32 v9, v7
	s_nop 0
	v_fma_f32 v11, -v7, v9, 1.0
	v_fmac_f32_e32 v9, v11, v9
	v_div_scale_f32 v11, vcc, v0, v3, v0
	v_mul_f32_e32 v12, v11, v9
	v_fma_f32 v13, -v7, v12, v11
	v_fmac_f32_e32 v12, v13, v9
	v_fma_f32 v7, -v7, v12, v11
	v_div_fmas_f32 v7, v7, v9, v12
	v_div_fixup_f32 v3, v7, v3, v0
	v_div_scale_f32 v0, s[0:1], v2, v2, v6
	v_rcp_f32_e32 v7, v0
	s_nop 0
	v_fma_f32 v9, -v0, v7, 1.0
	v_fmac_f32_e32 v7, v9, v7
	v_div_scale_f32 v9, vcc, v6, v2, v6
	v_mul_f32_e32 v11, v9, v7
	v_fma_f32 v12, -v0, v11, v9
	v_fmac_f32_e32 v11, v12, v7
	v_fma_f32 v0, -v0, v11, v9
	v_div_fmas_f32 v0, v0, v7, v11
	v_div_fixup_f32 v2, v0, v2, v6
	v_lshlrev_b32_e32 v6, 16, v1
	v_and_b32_e32 v7, 0xffff0000, v1
	v_mul_f32_e32 v0, 0xbfb8aa3b, v6
	v_mul_f32_e32 v1, 0xbfb8aa3b, v7
	v_exp_f32_e32 v0, v0
	v_exp_f32_e32 v1, v1
	v_pk_mul_f32 v[2:3], v[40:41], v[2:3]
	v_pk_add_f32 v[0:1], v[0:1], 1.0 op_sel_hi:[1,0]
	s_nop 0
	v_div_scale_f32 v9, s[0:1], v1, v1, v7
	v_rcp_f32_e32 v11, v9
	s_nop 0
	v_fma_f32 v12, -v9, v11, 1.0
	v_fmac_f32_e32 v11, v12, v11
	v_div_scale_f32 v12, vcc, v7, v1, v7
	v_mul_f32_e32 v13, v12, v11
	v_fma_f32 v14, -v9, v13, v12
	v_fmac_f32_e32 v13, v14, v11
	v_fma_f32 v9, -v9, v13, v12
	v_div_fmas_f32 v9, v9, v11, v13
	v_div_fixup_f32 v1, v9, v1, v7
	v_div_scale_f32 v7, s[0:1], v0, v0, v6
	v_rcp_f32_e32 v9, v7
	s_nop 0
	v_fma_f32 v11, -v7, v9, 1.0
	v_fmac_f32_e32 v9, v11, v9
	v_div_scale_f32 v11, vcc, v6, v0, v6
	v_mul_f32_e32 v12, v11, v9
	v_fma_f32 v13, -v7, v12, v11
	v_fmac_f32_e32 v12, v13, v9
	v_fma_f32 v7, -v7, v12, v11
	v_div_fmas_f32 v7, v7, v9, v12
	v_div_fixup_f32 v0, v7, v0, v6
	v_lshlrev_b32_e32 v9, 16, v8
	v_and_b32_e32 v8, 0xffff0000, v8
	v_pk_mul_f32 v[6:7], v[42:43], v[0:1]
	v_mul_f32_e32 v0, 0xbfb8aa3b, v9
	v_mul_f32_e32 v1, 0xbfb8aa3b, v8
	v_exp_f32_e32 v0, v0
	v_exp_f32_e32 v1, v1
	s_nop 0
	v_pk_add_f32 v[0:1], v[0:1], 1.0 op_sel_hi:[1,0]
	s_nop 0
	v_div_scale_f32 v11, s[0:1], v1, v1, v8
	v_rcp_f32_e32 v12, v11
	s_nop 0
	v_fma_f32 v13, -v11, v12, 1.0
	v_fmac_f32_e32 v12, v13, v12
	v_div_scale_f32 v13, vcc, v8, v1, v8
	v_mul_f32_e32 v14, v13, v12
	v_fma_f32 v15, -v11, v14, v13
	v_fmac_f32_e32 v14, v15, v12
	v_fma_f32 v11, -v11, v14, v13
	v_div_fmas_f32 v11, v11, v12, v14
	v_div_fixup_f32 v1, v11, v1, v8
	v_div_scale_f32 v8, s[0:1], v0, v0, v9
	v_rcp_f32_e32 v11, v8
	s_nop 0
	v_fma_f32 v12, -v8, v11, 1.0
	v_fmac_f32_e32 v11, v12, v11
	v_div_scale_f32 v12, vcc, v9, v0, v9
	v_mul_f32_e32 v13, v12, v11
	v_fma_f32 v14, -v8, v13, v12
	v_fmac_f32_e32 v13, v14, v11
	v_fma_f32 v8, -v8, v13, v12
	v_div_fmas_f32 v8, v8, v11, v13
	v_div_fixup_f32 v0, v8, v0, v9
	v_lshlrev_b32_e32 v11, 16, v10
	v_and_b32_e32 v10, 0xffff0000, v10
	v_pk_mul_f32 v[8:9], v[44:45], v[0:1]
	v_mul_f32_e32 v0, 0xbfb8aa3b, v11
	v_mul_f32_e32 v1, 0xbfb8aa3b, v10
	v_exp_f32_e32 v0, v0
	v_exp_f32_e32 v1, v1
	s_nop 0
	v_pk_add_f32 v[0:1], v[0:1], 1.0 op_sel_hi:[1,0]
	s_nop 0
	v_div_scale_f32 v12, s[0:1], v1, v1, v10
	v_rcp_f32_e32 v13, v12
	s_nop 0
	v_fma_f32 v14, -v12, v13, 1.0
	v_fmac_f32_e32 v13, v14, v13
	v_div_scale_f32 v14, vcc, v10, v1, v10
	v_mul_f32_e32 v15, v14, v13
	v_fma_f32 v16, -v12, v15, v14
	v_fmac_f32_e32 v15, v16, v13
	v_fma_f32 v12, -v12, v15, v14
	v_div_fmas_f32 v12, v12, v13, v15
	v_div_fixup_f32 v1, v12, v1, v10
	v_div_scale_f32 v10, s[0:1], v0, v0, v11
	v_rcp_f32_e32 v12, v10
	s_nop 0
	v_fma_f32 v13, -v10, v12, 1.0
	v_fmac_f32_e32 v12, v13, v12
	v_div_scale_f32 v13, vcc, v11, v0, v11
	v_mul_f32_e32 v14, v13, v12
	v_fma_f32 v15, -v10, v14, v13
	v_fmac_f32_e32 v14, v15, v12
	v_fma_f32 v10, -v10, v14, v13
	v_div_fmas_f32 v10, v10, v12, v14
	v_div_fixup_f32 v0, v10, v0, v11
	v_pk_mul_f32 v[10:11], v[46:47], v[0:1]
	v_cvt_pk_bf16_f32 v0, v2, v3
	v_cvt_pk_bf16_f32 v1, v6, v7
	v_cvt_pk_bf16_f32 v2, v8, v9
	v_cvt_pk_bf16_f32 v3, v10, v11
	s_nop 0
	v_permlane32_swap_b32_e32 v0, v2
	v_permlane32_swap_b32_e32 v1, v3
	global_store_dwordx4 v[4:5], v[0:3], off offset:96

.LBB0_714:
	v_cmp_lt_i32_e32 vcc, v109, v111
	v_lshlrev_b32_e32 v192, 1, v108
	v_readlane_b32 s76, v254, 37
	v_cndmask_b32_e32 v32, v110, v109, vcc
	v_lshlrev_b32_e32 v32, 2, v32
	ds_bpermute_b32 v32, v32, v34
	v_readlane_b32 s77, v254, 38
	s_waitcnt lgkmcnt(0)
	v_add_f32_e32 v32, v34, v32
	v_div_scale_f32 v33, s[0:1], v32, v32, 1.0
	v_rcp_f32_e32 v34, v33
	v_readlane_b32 s0, v254, 9
	v_readlane_b32 s1, v254, 10
	v_fma_f32 v35, -v33, v34, 1.0
	v_fmac_f32_e32 v34, v35, v34
	v_div_scale_f32 v35, vcc, 1.0, v32, 1.0
	v_mul_f32_e32 v36, v35, v34
	v_fma_f32 v37, -v33, v36, v35
	v_fmac_f32_e32 v36, v37, v34
	v_fma_f32 v33, -v33, v36, v35
	v_div_fmas_f32 v33, v33, v34, v36
	global_load_dwordx4 v[36:39], v[96:97], off offset:1536
	global_load_dwordx4 v[64:67], v[96:97], off offset:1568
	global_load_dwordx4 v[68:71], v[96:97], off offset:1600
	global_load_dwordx4 v[72:75], v[96:97], off offset:1632
	v_div_fixup_f32 v34, v33, v32, 1.0
	v_lshlrev_b64 v[32:33], 11, v[98:99]
	v_lshl_add_u64 v[32:33], s[0:1], 0, v[32:33]
	s_mov_b64 s[0:1], 0x3e38aa3b
	s_mov_b32 s15, s1
	v_lshl_add_u64 v[32:33], v[32:33], 0, s[14:15]
	v_lshl_add_u64 v[32:33], v[32:33], 0, v[192:193]
	s_waitcnt vmcnt(3)
	v_mov_b32_e32 v35, v38
	s_nop 1
	v_permlane32_swap_b32_e32 v36, v35
	v_lshlrev_b32_e32 v41, 16, v36
	v_and_b32_e32 v36, 0xffff0000, v36
	v_mov_b32_e32 v40, v39
	v_mul_f32_e32 v38, 0xbfb8aa3b, v41
	v_mul_f32_e32 v39, 0xbfb8aa3b, v36
	v_exp_f32_e32 v38, v38
	v_exp_f32_e32 v39, v39
	v_permlane32_swap_b32_e32 v37, v40
	v_pk_mul_f32 v[16:17], v[16:17], v[34:35] op_sel_hi:[1,0]
	v_pk_add_f32 v[38:39], v[38:39], 1.0 op_sel_hi:[1,0]
	v_pk_mul_f32 v[18:19], v[18:19], v[34:35] op_sel_hi:[1,0]
	v_div_scale_f32 v42, s[0:1], v39, v39, v36
	v_rcp_f32_e32 v43, v42
	s_nop 0
	v_fma_f32 v44, -v42, v43, 1.0
	v_fmac_f32_e32 v43, v44, v43
	v_div_scale_f32 v44, vcc, v36, v39, v36
	v_mul_f32_e32 v45, v44, v43
	v_fma_f32 v46, -v42, v45, v44
	v_fmac_f32_e32 v45, v46, v43
	v_fma_f32 v42, -v42, v45, v44
	v_div_fmas_f32 v42, v42, v43, v45
	v_div_fixup_f32 v39, v42, v39, v36
	v_div_scale_f32 v36, s[0:1], v38, v38, v41
	v_rcp_f32_e32 v42, v36
	s_nop 0
	v_fma_f32 v43, -v36, v42, 1.0
	v_fmac_f32_e32 v42, v43, v42
	v_div_scale_f32 v43, vcc, v41, v38, v41
	v_mul_f32_e32 v44, v43, v42
	v_fma_f32 v45, -v36, v44, v43
	v_fmac_f32_e32 v44, v45, v42
	v_fma_f32 v36, -v36, v44, v43
	v_div_fmas_f32 v36, v36, v42, v44
	v_div_fixup_f32 v38, v36, v38, v41
	v_pk_mul_f32 v[16:17], v[16:17], v[38:39]
	v_lshlrev_b32_e32 v38, 16, v37
	v_and_b32_e32 v39, 0xffff0000, v37
	v_mul_f32_e32 v36, 0xbfb8aa3b, v38
	v_mul_f32_e32 v37, 0xbfb8aa3b, v39
	v_exp_f32_e32 v36, v36
	v_exp_f32_e32 v37, v37
	v_cvt_pk_bf16_f32 v16, v16, v17
	v_pk_add_f32 v[36:37], v[36:37], 1.0 op_sel_hi:[1,0]
	s_nop 0
	v_div_scale_f32 v41, s[0:1], v37, v37, v39
	v_rcp_f32_e32 v42, v41
	s_nop 0
	v_fma_f32 v43, -v41, v42, 1.0
	v_fmac_f32_e32 v42, v43, v42
	v_div_scale_f32 v43, vcc, v39, v37, v39
	v_mul_f32_e32 v44, v43, v42
	v_fma_f32 v45, -v41, v44, v43
	v_fmac_f32_e32 v44, v45, v42
	v_fma_f32 v41, -v41, v44, v43
	v_div_fmas_f32 v41, v41, v42, v44
	v_div_fixup_f32 v37, v41, v37, v39
	v_div_scale_f32 v39, s[0:1], v36, v36, v38
	v_rcp_f32_e32 v41, v39
	s_nop 0
	v_fma_f32 v42, -v39, v41, 1.0
	v_fmac_f32_e32 v41, v42, v41
	v_div_scale_f32 v42, vcc, v38, v36, v38
	v_mul_f32_e32 v43, v42, v41
	v_fma_f32 v44, -v39, v43, v42
	v_fmac_f32_e32 v43, v44, v41
	v_fma_f32 v39, -v39, v43, v42
	v_div_fmas_f32 v39, v39, v41, v43
	v_div_fixup_f32 v36, v39, v36, v38
	v_lshlrev_b32_e32 v38, 16, v35
	v_and_b32_e32 v35, 0xffff0000, v35
	v_pk_mul_f32 v[18:19], v[18:19], v[36:37]
	v_mul_f32_e32 v36, 0xbfb8aa3b, v38
	v_mul_f32_e32 v37, 0xbfb8aa3b, v35
	v_exp_f32_e32 v36, v36
	v_exp_f32_e32 v37, v37
	v_pk_mul_f32 v[20:21], v[20:21], v[34:35] op_sel_hi:[1,0]
	v_cvt_pk_bf16_f32 v17, v18, v19
	v_pk_add_f32 v[36:37], v[36:37], 1.0 op_sel_hi:[1,0]
	s_nop 0
	v_div_scale_f32 v39, s[0:1], v37, v37, v35
	v_rcp_f32_e32 v41, v39
	s_nop 0
	v_fma_f32 v42, -v39, v41, 1.0
	v_fmac_f32_e32 v41, v42, v41
	v_div_scale_f32 v42, vcc, v35, v37, v35
	v_mul_f32_e32 v43, v42, v41
	v_fma_f32 v44, -v39, v43, v42
	v_fmac_f32_e32 v43, v44, v41
	v_fma_f32 v39, -v39, v43, v42
	v_div_fmas_f32 v39, v39, v41, v43
	v_div_fixup_f32 v37, v39, v37, v35
	v_div_scale_f32 v35, s[0:1], v36, v36, v38
	v_rcp_f32_e32 v39, v35
	s_nop 0
	v_fma_f32 v41, -v35, v39, 1.0
	v_fmac_f32_e32 v39, v41, v39
	v_div_scale_f32 v41, vcc, v38, v36, v38
	v_mul_f32_e32 v42, v41, v39
	v_fma_f32 v43, -v35, v42, v41
	v_fmac_f32_e32 v42, v43, v39
	v_fma_f32 v35, -v35, v42, v41
	v_div_fmas_f32 v35, v35, v39, v42
	v_div_fixup_f32 v36, v35, v36, v38
	v_lshlrev_b32_e32 v35, 16, v40
	v_and_b32_e32 v38, 0xffff0000, v40
	v_pk_mul_f32 v[20:21], v[20:21], v[36:37]
	v_mul_f32_e32 v36, 0xbfb8aa3b, v35
	v_mul_f32_e32 v37, 0xbfb8aa3b, v38
	v_exp_f32_e32 v36, v36
	v_exp_f32_e32 v37, v37
	v_pk_mul_f32 v[22:23], v[22:23], v[34:35] op_sel_hi:[1,0]
	v_cvt_pk_bf16_f32 v18, v20, v21
	s_nop 1
	v_permlane32_swap_b32_e32 v16, v18
	v_pk_add_f32 v[36:37], v[36:37], 1.0 op_sel_hi:[1,0]
	s_nop 0
	v_div_scale_f32 v39, s[0:1], v37, v37, v38
	v_rcp_f32_e32 v40, v39
	s_nop 0
	v_fma_f32 v41, -v39, v40, 1.0
	v_fmac_f32_e32 v40, v41, v40
	v_div_scale_f32 v41, vcc, v38, v37, v38
	v_mul_f32_e32 v42, v41, v40
	v_fma_f32 v43, -v39, v42, v41
	v_fmac_f32_e32 v42, v43, v40
	v_fma_f32 v39, -v39, v42, v41
	v_div_fmas_f32 v39, v39, v40, v42
	v_div_fixup_f32 v37, v39, v37, v38
	v_div_scale_f32 v38, s[0:1], v36, v36, v35
	v_rcp_f32_e32 v39, v38
	s_nop 0
	v_fma_f32 v40, -v38, v39, 1.0
	v_fmac_f32_e32 v39, v40, v39
	v_div_scale_f32 v40, vcc, v35, v36, v35
	v_mul_f32_e32 v41, v40, v39
	v_fma_f32 v42, -v38, v41, v40
	v_fmac_f32_e32 v41, v42, v39
	v_fma_f32 v38, -v38, v41, v40
	v_div_fmas_f32 v38, v38, v39, v41
	v_div_fixup_f32 v36, v38, v36, v35
	v_pk_mul_f32 v[22:23], v[22:23], v[36:37]
	s_nop 0
	v_cvt_pk_bf16_f32 v19, v22, v23
	s_nop 1
	v_permlane32_swap_b32_e32 v17, v19
	global_store_dwordx4 v[32:33], v[16:19], off
	s_waitcnt vmcnt(3)
	v_mov_b32_e32 v22, v66
	s_nop 1
	v_mov_b32_e32 v16, v64
	s_nop 1
	v_permlane32_swap_b32_e32 v16, v22
	v_lshlrev_b32_e32 v23, 16, v16
	v_and_b32_e32 v16, 0xffff0000, v16
	v_mul_f32_e32 v20, 0xbfb8aa3b, v23
	v_mul_f32_e32 v21, 0xbfb8aa3b, v16
	v_exp_f32_e32 v20, v20
	v_exp_f32_e32 v21, v21
	v_mov_b32_e32 v35, v67
	s_nop 1
	v_mov_b32_e32 v17, v65
	s_nop 1
	v_permlane32_swap_b32_e32 v17, v35
	v_pk_add_f32 v[20:21], v[20:21], 1.0 op_sel_hi:[1,0]
	v_pk_mul_f32 v[18:19], v[24:25], v[34:35] op_sel_hi:[1,0]
	v_div_scale_f32 v24, s[0:1], v21, v21, v16
	v_rcp_f32_e32 v25, v24
	s_nop 0
	v_fma_f32 v36, -v24, v25, 1.0
	v_fmac_f32_e32 v25, v36, v25
	v_div_scale_f32 v36, vcc, v16, v21, v16
	v_mul_f32_e32 v37, v36, v25
	v_fma_f32 v38, -v24, v37, v36
	v_fmac_f32_e32 v37, v38, v25
	v_fma_f32 v24, -v24, v37, v36
	v_div_fmas_f32 v24, v24, v25, v37
	v_div_fixup_f32 v21, v24, v21, v16
	v_div_scale_f32 v16, s[0:1], v20, v20, v23
	v_rcp_f32_e32 v24, v16
	s_nop 0
	v_fma_f32 v25, -v16, v24, 1.0
	v_fmac_f32_e32 v24, v25, v24
	v_div_scale_f32 v25, vcc, v23, v20, v23
	v_mul_f32_e32 v36, v25, v24
	v_fma_f32 v37, -v16, v36, v25
	v_fmac_f32_e32 v36, v37, v24
	v_fma_f32 v16, -v16, v36, v25
	v_div_fmas_f32 v16, v16, v24, v36
	v_div_fixup_f32 v20, v16, v20, v23
	v_lshlrev_b32_e32 v23, 16, v17
	v_and_b32_e32 v24, 0xffff0000, v17
	v_pk_mul_f32 v[18:19], v[18:19], v[20:21]
	v_mul_f32_e32 v20, 0xbfb8aa3b, v23
	v_mul_f32_e32 v21, 0xbfb8aa3b, v24
	v_exp_f32_e32 v20, v20
	v_exp_f32_e32 v21, v21
	v_pk_mul_f32 v[16:17], v[26:27], v[34:35] op_sel_hi:[1,0]
	v_pk_add_f32 v[20:21], v[20:21], 1.0 op_sel_hi:[1,0]
	s_nop 0
	v_div_scale_f32 v25, s[0:1], v21, v21, v24
	v_rcp_f32_e32 v26, v25
	s_nop 0
	v_fma_f32 v27, -v25, v26, 1.0
	v_fmac_f32_e32 v26, v27, v26
	v_div_scale_f32 v27, vcc, v24, v21, v24
	v_mul_f32_e32 v36, v27, v26
	v_fma_f32 v37, -v25, v36, v27
	v_fmac_f32_e32 v36, v37, v26
	v_fma_f32 v25, -v25, v36, v27
	v_div_fmas_f32 v25, v25, v26, v36
	v_div_fixup_f32 v21, v25, v21, v24
	v_div_scale_f32 v24, s[0:1], v20, v20, v23
	v_rcp_f32_e32 v25, v24
	s_nop 0
	v_fma_f32 v26, -v24, v25, 1.0
	v_fmac_f32_e32 v25, v26, v25
	v_div_scale_f32 v26, vcc, v23, v20, v23
	v_mul_f32_e32 v27, v26, v25
	v_fma_f32 v36, -v24, v27, v26
	v_fmac_f32_e32 v27, v36, v25
	v_fma_f32 v24, -v24, v27, v26
	v_div_fmas_f32 v24, v24, v25, v27
	v_div_fixup_f32 v20, v24, v20, v23
	v_lshlrev_b32_e32 v24, 16, v22
	v_and_b32_e32 v25, 0xffff0000, v22
	v_mul_f32_e32 v22, 0xbfb8aa3b, v24
	v_mul_f32_e32 v23, 0xbfb8aa3b, v25
	v_exp_f32_e32 v22, v22
	v_exp_f32_e32 v23, v23
	v_pk_mul_f32 v[20:21], v[16:17], v[20:21]
	v_pk_mul_f32 v[16:17], v[28:29], v[34:35] op_sel_hi:[1,0]
	v_pk_add_f32 v[22:23], v[22:23], 1.0 op_sel_hi:[1,0]
	s_nop 0
	v_div_scale_f32 v26, s[0:1], v23, v23, v25
	v_rcp_f32_e32 v27, v26
	s_nop 0
	v_fma_f32 v28, -v26, v27, 1.0
	v_fmac_f32_e32 v27, v28, v27
	v_div_scale_f32 v28, vcc, v25, v23, v25
	v_mul_f32_e32 v29, v28, v27
	v_fma_f32 v36, -v26, v29, v28
	v_fmac_f32_e32 v29, v36, v27
	v_fma_f32 v26, -v26, v29, v28
	v_div_fmas_f32 v26, v26, v27, v29
	v_div_fixup_f32 v23, v26, v23, v25
	v_div_scale_f32 v25, s[0:1], v22, v22, v24
	v_rcp_f32_e32 v26, v25
	s_nop 0
	v_fma_f32 v27, -v25, v26, 1.0
	v_fmac_f32_e32 v26, v27, v26
	v_div_scale_f32 v27, vcc, v24, v22, v24
	v_mul_f32_e32 v28, v27, v26
	v_fma_f32 v29, -v25, v28, v27
	v_fmac_f32_e32 v28, v29, v26
	v_fma_f32 v25, -v25, v28, v27
	v_div_fmas_f32 v25, v25, v26, v28
	v_lshlrev_b32_e32 v26, 16, v35
	v_and_b32_e32 v27, 0xffff0000, v35
	v_div_fixup_f32 v22, v25, v22, v24
	v_mul_f32_e32 v24, 0xbfb8aa3b, v26
	v_mul_f32_e32 v25, 0xbfb8aa3b, v27
	v_exp_f32_e32 v24, v24
	v_exp_f32_e32 v25, v25
	v_pk_mul_f32 v[22:23], v[16:17], v[22:23]
	v_pk_mul_f32 v[16:17], v[30:31], v[34:35] op_sel_hi:[1,0]
	v_pk_add_f32 v[24:25], v[24:25], 1.0 op_sel_hi:[1,0]
	s_nop 0
	v_div_scale_f32 v28, s[0:1], v25, v25, v27
	v_rcp_f32_e32 v29, v28
	s_nop 0
	v_fma_f32 v30, -v28, v29, 1.0
	v_fmac_f32_e32 v29, v30, v29
	v_div_scale_f32 v30, vcc, v27, v25, v27
	v_mul_f32_e32 v31, v30, v29
	v_fma_f32 v35, -v28, v31, v30
	v_fmac_f32_e32 v31, v35, v29
	v_fma_f32 v28, -v28, v31, v30
	v_div_fmas_f32 v28, v28, v29, v31
	v_div_fixup_f32 v25, v28, v25, v27
	v_div_scale_f32 v27, s[0:1], v24, v24, v26
	v_rcp_f32_e32 v28, v27
	v_pk_mul_f32 v[0:1], v[0:1], v[34:35] op_sel_hi:[1,0]
	v_pk_mul_f32 v[2:3], v[2:3], v[34:35] op_sel_hi:[1,0]
	v_pk_mul_f32 v[4:5], v[4:5], v[34:35] op_sel_hi:[1,0]
	v_fma_f32 v29, -v27, v28, 1.0
	v_fmac_f32_e32 v28, v29, v28
	v_div_scale_f32 v29, vcc, v26, v24, v26
	v_mul_f32_e32 v30, v29, v28
	v_fma_f32 v31, -v27, v30, v29
	v_fmac_f32_e32 v30, v31, v28
	v_fma_f32 v27, -v27, v30, v29
	v_div_fmas_f32 v27, v27, v28, v30
	v_div_fixup_f32 v24, v27, v24, v26
	v_pk_mul_f32 v[24:25], v[16:17], v[24:25]
	v_cvt_pk_bf16_f32 v16, v18, v19
	v_cvt_pk_bf16_f32 v17, v20, v21
	v_cvt_pk_bf16_f32 v18, v22, v23
	v_cvt_pk_bf16_f32 v19, v24, v25
	s_nop 0
	v_permlane32_swap_b32_e32 v16, v18
	v_permlane32_swap_b32_e32 v17, v19
	global_store_dwordx4 v[32:33], v[16:19], off offset:32
	v_pk_mul_f32 v[6:7], v[6:7], v[34:35] op_sel_hi:[1,0]
	s_waitcnt vmcnt(3)
	v_mov_b32_e32 v20, v70
	s_nop 1
	v_mov_b32_e32 v16, v68
	s_nop 1
	v_permlane32_swap_b32_e32 v16, v20
	v_lshlrev_b32_e32 v22, 16, v16
	v_and_b32_e32 v16, 0xffff0000, v16
	v_mov_b32_e32 v21, v71
	v_mul_f32_e32 v18, 0xbfb8aa3b, v22
	v_mul_f32_e32 v19, 0xbfb8aa3b, v16
	v_exp_f32_e32 v18, v18
	v_exp_f32_e32 v19, v19
	v_mov_b32_e32 v17, v69
	s_nop 1
	v_permlane32_swap_b32_e32 v17, v21
	v_pk_add_f32 v[18:19], v[18:19], 1.0 op_sel_hi:[1,0]
	s_nop 0
	v_div_scale_f32 v23, s[0:1], v19, v19, v16
	v_rcp_f32_e32 v24, v23
	s_nop 0
	v_fma_f32 v25, -v23, v24, 1.0
	v_fmac_f32_e32 v24, v25, v24
	v_div_scale_f32 v25, vcc, v16, v19, v16
	v_mul_f32_e32 v26, v25, v24
	v_fma_f32 v27, -v23, v26, v25
	v_fmac_f32_e32 v26, v27, v24
	v_fma_f32 v23, -v23, v26, v25
	v_div_fmas_f32 v23, v23, v24, v26
	v_div_fixup_f32 v19, v23, v19, v16
	v_div_scale_f32 v16, s[0:1], v18, v18, v22
	v_rcp_f32_e32 v23, v16
	s_nop 0
	v_fma_f32 v24, -v16, v23, 1.0
	v_fmac_f32_e32 v23, v24, v23
	v_div_scale_f32 v24, vcc, v22, v18, v22
	v_mul_f32_e32 v25, v24, v23
	v_fma_f32 v26, -v16, v25, v24
	v_fmac_f32_e32 v25, v26, v23
	v_fma_f32 v16, -v16, v25, v24
	v_div_fmas_f32 v16, v16, v23, v25
	v_div_fixup_f32 v18, v16, v18, v22
	v_pk_mul_f32 v[0:1], v[0:1], v[18:19]
	v_lshlrev_b32_e32 v18, 16, v17
	v_and_b32_e32 v19, 0xffff0000, v17
	v_mul_f32_e32 v16, 0xbfb8aa3b, v18
	v_mul_f32_e32 v17, 0xbfb8aa3b, v19
	v_exp_f32_e32 v16, v16
	v_exp_f32_e32 v17, v17
	v_cvt_pk_bf16_f32 v0, v0, v1
	v_pk_add_f32 v[16:17], v[16:17], 1.0 op_sel_hi:[1,0]
	s_nop 0
	v_div_scale_f32 v22, s[0:1], v17, v17, v19
	v_rcp_f32_e32 v23, v22
	s_nop 0
	v_fma_f32 v24, -v22, v23, 1.0
	v_fmac_f32_e32 v23, v24, v23
	v_div_scale_f32 v24, vcc, v19, v17, v19
	v_mul_f32_e32 v25, v24, v23
	v_fma_f32 v26, -v22, v25, v24
	v_fmac_f32_e32 v25, v26, v23
	v_fma_f32 v22, -v22, v25, v24
	v_div_fmas_f32 v22, v22, v23, v25
	v_div_fixup_f32 v17, v22, v17, v19
	v_div_scale_f32 v19, s[0:1], v16, v16, v18
	v_rcp_f32_e32 v22, v19
	s_nop 0
	v_fma_f32 v23, -v19, v22, 1.0
	v_fmac_f32_e32 v22, v23, v22
	v_div_scale_f32 v23, vcc, v18, v16, v18
	v_mul_f32_e32 v24, v23, v22
	v_fma_f32 v25, -v19, v24, v23
	v_fmac_f32_e32 v24, v25, v22
	v_fma_f32 v19, -v19, v24, v23
	v_div_fmas_f32 v19, v19, v22, v24
	v_div_fixup_f32 v16, v19, v16, v18
	v_lshlrev_b32_e32 v18, 16, v20
	v_and_b32_e32 v19, 0xffff0000, v20
	v_pk_mul_f32 v[2:3], v[2:3], v[16:17]
	v_mul_f32_e32 v16, 0xbfb8aa3b, v18
	v_mul_f32_e32 v17, 0xbfb8aa3b, v19
	v_exp_f32_e32 v16, v16
	v_exp_f32_e32 v17, v17
	v_cvt_pk_bf16_f32 v1, v2, v3
	v_pk_add_f32 v[16:17], v[16:17], 1.0 op_sel_hi:[1,0]
	s_nop 0
	v_div_scale_f32 v20, s[0:1], v17, v17, v19
	v_rcp_f32_e32 v22, v20
	s_nop 0
	v_fma_f32 v23, -v20, v22, 1.0
	v_fmac_f32_e32 v22, v23, v22
	v_div_scale_f32 v23, vcc, v19, v17, v19
	v_mul_f32_e32 v24, v23, v22
	v_fma_f32 v25, -v20, v24, v23
	v_fmac_f32_e32 v24, v25, v22
	v_fma_f32 v20, -v20, v24, v23
	v_div_fmas_f32 v20, v20, v22, v24
	v_div_fixup_f32 v17, v20, v17, v19
	v_div_scale_f32 v19, s[0:1], v16, v16, v18
	v_rcp_f32_e32 v20, v19
	s_nop 0
	v_fma_f32 v22, -v19, v20, 1.0
	v_fmac_f32_e32 v20, v22, v20
	v_div_scale_f32 v22, vcc, v18, v16, v18
	v_mul_f32_e32 v23, v22, v20
	v_fma_f32 v24, -v19, v23, v22
	v_fmac_f32_e32 v23, v24, v20
	v_fma_f32 v19, -v19, v23, v22
	v_div_fmas_f32 v19, v19, v20, v23
	v_div_fixup_f32 v16, v19, v16, v18
	v_lshlrev_b32_e32 v18, 16, v21
	v_and_b32_e32 v19, 0xffff0000, v21
	v_pk_mul_f32 v[4:5], v[4:5], v[16:17]
	v_mul_f32_e32 v16, 0xbfb8aa3b, v18
	v_mul_f32_e32 v17, 0xbfb8aa3b, v19
	v_exp_f32_e32 v16, v16
	v_exp_f32_e32 v17, v17
	v_cvt_pk_bf16_f32 v2, v4, v5
	s_nop 1
	v_permlane32_swap_b32_e32 v0, v2
	v_pk_add_f32 v[16:17], v[16:17], 1.0 op_sel_hi:[1,0]
	s_nop 0
	v_div_scale_f32 v20, s[0:1], v17, v17, v19
	v_rcp_f32_e32 v21, v20
	s_nop 0
	v_fma_f32 v22, -v20, v21, 1.0
	v_fmac_f32_e32 v21, v22, v21
	v_div_scale_f32 v22, vcc, v19, v17, v19
	v_mul_f32_e32 v23, v22, v21
	v_fma_f32 v24, -v20, v23, v22
	v_fmac_f32_e32 v23, v24, v21
	v_fma_f32 v20, -v20, v23, v22
	v_div_fmas_f32 v20, v20, v21, v23
	v_div_fixup_f32 v17, v20, v17, v19
	v_div_scale_f32 v19, s[0:1], v16, v16, v18
	v_rcp_f32_e32 v20, v19
	s_nop 0
	v_fma_f32 v21, -v19, v20, 1.0
	v_fmac_f32_e32 v20, v21, v20
	v_div_scale_f32 v21, vcc, v18, v16, v18
	v_mul_f32_e32 v22, v21, v20
	v_fma_f32 v23, -v19, v22, v21
	v_fmac_f32_e32 v22, v23, v20
	v_fma_f32 v19, -v19, v22, v21
	v_div_fmas_f32 v19, v19, v20, v22
	v_div_fixup_f32 v16, v19, v16, v18
	v_pk_mul_f32 v[6:7], v[6:7], v[16:17]
	s_nop 0
	v_cvt_pk_bf16_f32 v3, v6, v7
	s_nop 1
	v_permlane32_swap_b32_e32 v1, v3
	global_store_dwordx4 v[32:33], v[0:3], off offset:64
	s_waitcnt vmcnt(3)
	v_mov_b32_e32 v6, v74
	s_nop 1
	v_mov_b32_e32 v0, v72
	s_nop 1
	v_permlane32_swap_b32_e32 v0, v6
	v_lshlrev_b32_e32 v7, 16, v0
	v_and_b32_e32 v0, 0xffff0000, v0
	v_mul_f32_e32 v4, 0xbfb8aa3b, v7
	v_mul_f32_e32 v5, 0xbfb8aa3b, v0
	v_exp_f32_e32 v4, v4
	v_exp_f32_e32 v5, v5
	v_mov_b32_e32 v16, v75
	v_pk_mul_f32 v[2:3], v[8:9], v[34:35] op_sel_hi:[1,0]
	s_nop 0
	v_mov_b32_e32 v1, v73
	s_nop 1
	v_permlane32_swap_b32_e32 v1, v16
	v_pk_add_f32 v[4:5], v[4:5], 1.0 op_sel_hi:[1,0]
	s_nop 0
	v_div_scale_f32 v8, s[0:1], v5, v5, v0
	v_rcp_f32_e32 v9, v8
	s_nop 0
	v_fma_f32 v17, -v8, v9, 1.0
	v_fmac_f32_e32 v9, v17, v9
	v_div_scale_f32 v17, vcc, v0, v5, v0
	v_mul_f32_e32 v18, v17, v9
	v_fma_f32 v19, -v8, v18, v17
	v_fmac_f32_e32 v18, v19, v9
	v_fma_f32 v8, -v8, v18, v17
	v_div_fmas_f32 v8, v8, v9, v18
	v_div_fixup_f32 v5, v8, v5, v0
	v_div_scale_f32 v0, s[0:1], v4, v4, v7
	v_rcp_f32_e32 v8, v0
	s_nop 0
	v_fma_f32 v9, -v0, v8, 1.0
	v_fmac_f32_e32 v8, v9, v8
	v_div_scale_f32 v9, vcc, v7, v4, v7
	v_mul_f32_e32 v17, v9, v8
	v_fma_f32 v18, -v0, v17, v9
	v_fmac_f32_e32 v17, v18, v8
	v_fma_f32 v0, -v0, v17, v9
	v_div_fmas_f32 v0, v0, v8, v17
	v_div_fixup_f32 v4, v0, v4, v7
	v_lshlrev_b32_e32 v7, 16, v1
	v_and_b32_e32 v8, 0xffff0000, v1
	v_pk_mul_f32 v[2:3], v[2:3], v[4:5]
	v_mul_f32_e32 v4, 0xbfb8aa3b, v7
	v_mul_f32_e32 v5, 0xbfb8aa3b, v8
	v_exp_f32_e32 v4, v4
	v_exp_f32_e32 v5, v5
	v_pk_mul_f32 v[0:1], v[10:11], v[34:35] op_sel_hi:[1,0]
	v_pk_add_f32 v[4:5], v[4:5], 1.0 op_sel_hi:[1,0]
	s_nop 0
	v_div_scale_f32 v9, s[0:1], v5, v5, v8
	v_rcp_f32_e32 v10, v9
	s_nop 0
	v_fma_f32 v11, -v9, v10, 1.0
	v_fmac_f32_e32 v10, v11, v10
	v_div_scale_f32 v11, vcc, v8, v5, v8
	v_mul_f32_e32 v17, v11, v10
	v_fma_f32 v18, -v9, v17, v11
	v_fmac_f32_e32 v17, v18, v10
	v_fma_f32 v9, -v9, v17, v11
	v_div_fmas_f32 v9, v9, v10, v17
	v_div_fixup_f32 v5, v9, v5, v8
	v_div_scale_f32 v8, s[0:1], v4, v4, v7
	v_rcp_f32_e32 v9, v8
	s_nop 0
	v_fma_f32 v10, -v8, v9, 1.0
	v_fmac_f32_e32 v9, v10, v9
	v_div_scale_f32 v10, vcc, v7, v4, v7
	v_mul_f32_e32 v11, v10, v9
	v_fma_f32 v17, -v8, v11, v10
	v_fmac_f32_e32 v11, v17, v9
	v_fma_f32 v8, -v8, v11, v10
	v_div_fmas_f32 v8, v8, v9, v11
	v_div_fixup_f32 v4, v8, v4, v7
	v_lshlrev_b32_e32 v8, 16, v6
	v_and_b32_e32 v9, 0xffff0000, v6
	v_mul_f32_e32 v6, 0xbfb8aa3b, v8
	v_mul_f32_e32 v7, 0xbfb8aa3b, v9
	v_exp_f32_e32 v6, v6
	v_exp_f32_e32 v7, v7
	v_pk_mul_f32 v[4:5], v[0:1], v[4:5]
	v_pk_mul_f32 v[0:1], v[12:13], v[34:35] op_sel_hi:[1,0]
	v_pk_add_f32 v[6:7], v[6:7], 1.0 op_sel_hi:[1,0]
	s_nop 0
	v_div_scale_f32 v10, s[0:1], v7, v7, v9
	v_rcp_f32_e32 v11, v10
	s_nop 0
	v_fma_f32 v12, -v10, v11, 1.0
	v_fmac_f32_e32 v11, v12, v11
	v_div_scale_f32 v12, vcc, v9, v7, v9
	v_mul_f32_e32 v13, v12, v11
	v_fma_f32 v17, -v10, v13, v12
	v_fmac_f32_e32 v13, v17, v11
	v_fma_f32 v10, -v10, v13, v12
	v_div_fmas_f32 v10, v10, v11, v13
	v_div_fixup_f32 v7, v10, v7, v9
	v_div_scale_f32 v9, s[0:1], v6, v6, v8
	v_rcp_f32_e32 v10, v9
	s_nop 0
	v_fma_f32 v11, -v9, v10, 1.0
	v_fmac_f32_e32 v10, v11, v10
	v_div_scale_f32 v11, vcc, v8, v6, v8
	v_mul_f32_e32 v12, v11, v10
	v_fma_f32 v13, -v9, v12, v11
	v_fmac_f32_e32 v12, v13, v10
	v_fma_f32 v9, -v9, v12, v11
	v_div_fmas_f32 v9, v9, v10, v12
	v_lshlrev_b32_e32 v10, 16, v16
	v_and_b32_e32 v11, 0xffff0000, v16
	v_div_fixup_f32 v6, v9, v6, v8
	v_mul_f32_e32 v8, 0xbfb8aa3b, v10
	v_mul_f32_e32 v9, 0xbfb8aa3b, v11
	v_exp_f32_e32 v8, v8
	v_exp_f32_e32 v9, v9
	v_pk_mul_f32 v[6:7], v[0:1], v[6:7]
	v_pk_mul_f32 v[0:1], v[14:15], v[34:35] op_sel_hi:[1,0]
	v_pk_add_f32 v[8:9], v[8:9], 1.0 op_sel_hi:[1,0]
	s_nop 0
	v_div_scale_f32 v12, s[0:1], v9, v9, v11
	v_rcp_f32_e32 v13, v12
	s_nop 0
	v_fma_f32 v14, -v12, v13, 1.0
	v_fmac_f32_e32 v13, v14, v13
	v_div_scale_f32 v14, vcc, v11, v9, v11
	v_mul_f32_e32 v15, v14, v13
	v_fma_f32 v16, -v12, v15, v14
	v_fmac_f32_e32 v15, v16, v13
	v_fma_f32 v12, -v12, v15, v14
	v_div_fmas_f32 v12, v12, v13, v15
	v_div_fixup_f32 v9, v12, v9, v11
	v_div_scale_f32 v11, s[0:1], v8, v8, v10
	v_rcp_f32_e32 v12, v11
	s_nop 0
	v_fma_f32 v13, -v11, v12, 1.0
	v_fmac_f32_e32 v12, v13, v12
	v_div_scale_f32 v13, vcc, v10, v8, v10
	v_mul_f32_e32 v14, v13, v12
	v_fma_f32 v15, -v11, v14, v13
	v_fmac_f32_e32 v14, v15, v12
	v_fma_f32 v11, -v11, v14, v13
	v_div_fmas_f32 v11, v11, v12, v14
	v_div_fixup_f32 v8, v11, v8, v10
	v_pk_mul_f32 v[8:9], v[0:1], v[8:9]
	v_cvt_pk_bf16_f32 v0, v2, v3
	v_cvt_pk_bf16_f32 v1, v4, v5
	v_cvt_pk_bf16_f32 v2, v6, v7
	v_cvt_pk_bf16_f32 v3, v8, v9
	s_nop 0
	v_permlane32_swap_b32_e32 v0, v2
	v_permlane32_swap_b32_e32 v1, v3
	global_store_dwordx4 v[32:33], v[0:3], off offset:96
